# rnn unit loops: conv and gelu LDS reads issued up front, store-ack waits at loop top removed
# speedup vs baseline: 1.0018x; 1.0018x over previous
; __device__ __forceinline__ unsigned cvt_pk_bf16(float lo, float hi) { unsigned r; asm volatile("v_cvt_pk_bf16_f32 %0, %1, %2" : "=v"(r) : "v"(lo), "v"(hi)); return r; }
; #define LAS __attribute__((address_space(3)))
; template <int MODE>
; __device__ __forceinline__ void rnn_phase(const RnnP& P, LAS unsigned char* lds, int G, int bid, int nunits) {
;     ...
;         { float x3, x2, x1;
;           if (samp) { const float* sc = P.st_conv + (size_t)((R0 >> 4) + rg) * 3 * 2048 + chg; x3 = sc[0]; x2 = sc[2048]; x1 = sc[4096]; }
;           else { x3 = XRF[(16 * rg + 0) * 128 + ch]; x2 = XRF[(16 * rg + 1) * 128 + ch]; x1 = XRF[(16 * rg + 2) * 128 + ch]; }
; #pragma unroll
;           for (int i = 0; i < 16; ++i) { const float x0 = XRF[(16 * rg + 3 + i) * 128 + ch]; xc[i] = __builtin_fmaf(w3, x0, __builtin_fmaf(w2, x1, __builtin_fmaf(w1, x2, __builtin_fmaf(w0, x3, bc)))); x3 = x2; x2 = x1; x1 = x0;
;               XCB[(16 * rg + i) * 136 + ch] = (bf16)pg8::cvt_pk_bf16(xc[i], xc[i]); } }
;         __syncthreads();
; #pragma unroll
;         for (int mt = 0; mt < 4; ++mt) { f32x4 d0 = (f32x4){0.f, 0.f, 0.f, 0.f}, d1 = d0;
; #pragma unroll
;             for (int kk = 0; kk < 4; ++kk) { const bf16x8 a = *(const LAS bf16x8*)(XCB + (16 * mt + jj) * 136 + 32 * kk + 8 * q);
;                 d0 = __builtin_amdgcn_mfma_f32_16x16x32_bf16(a, Bf[0][kk], d0, 0, 0, 0); d1 = __builtin_amdgcn_mfma_f32_16x16x32_bf16(a, Bf[1][kk], d1, 0, 0, 0); }
; #pragma unroll
;             for (int ep = 0; ep < 2; ++ep) { const int row = 16 * mt + 4 * q + 2 * ep;
;                 const f32x2 t0 = (f32x2){d0[2 * ep], d0[2 * ep + 1]} * (f32x2){-1.4426950408889634f, -1.4426950408889634f} + (f32x2){nb0, nb0};
;                 const f32x2 t1 = (f32x2){d1[2 * ep], d1[2 * ep + 1]} * (f32x2){-1.4426950408889634f, -1.4426950408889634f} + (f32x2){nb1, nb1};
;                 const f32x2 e0 = (f32x2){__builtin_amdgcn_exp2f(t0.x), __builtin_amdgcn_exp2f(t0.y)} + (f32x2){1.f, 1.f}, e1 = (f32x2){__builtin_amdgcn_exp2f(t1.x), __builtin_amdgcn_exp2f(t1.y)} + (f32x2){1.f, 1.f};
;                 GT[(gate * 64 + row) * GTP + cb + jj] = __builtin_amdgcn_rcpf(e0.x); GT[(gate * 64 + row + 1) * GTP + cb + jj] = __builtin_amdgcn_rcpf(e0.y);
;                 GT[(gate * 64 + row) * GTP + cb + 16 + jj] = __builtin_amdgcn_rcpf(e1.x); GT[(gate * 64 + row + 1) * GTP + cb + 16 + jj] = __builtin_amdgcn_rcpf(e1.y); } }
.LBB0_1214:
	s_waitcnt lgkmcnt(0)
	s_barrier
	ds_read2st64_b32 v[58:59], v77 offset1:2
	ds_read2st64_b32 v[60:61], v77 offset0:4 offset1:6
	ds_read_b32 v128, v77 offset:2048
	ds_read_b32 v129, v77 offset:2560
	ds_read_b32 v130, v77 offset:3072
	ds_read_b32 v131, v77 offset:3584
	ds_read_b32 v132, v77 offset:4096
	ds_read_b32 v133, v77 offset:4608
	ds_read_b32 v134, v77 offset:5120
	ds_read_b32 v135, v77 offset:5632
	ds_read_b32 v136, v77 offset:6144
	ds_read_b32 v137, v77 offset:6656
	ds_read_b32 v138, v77 offset:7168
	ds_read_b32 v139, v77 offset:7680
	ds_read_b32 v140, v77 offset:8192
	ds_read_b32 v141, v77 offset:8704
	ds_read_b32 v142, v77 offset:9216
	s_waitcnt vmcnt(3) lgkmcnt(1)
	v_fma_f32 v72, v111, v58, v107
	s_waitcnt vmcnt(2)
	v_fmac_f32_e32 v72, v110, v59
	s_waitcnt vmcnt(1) lgkmcnt(0)
	v_fmac_f32_e32 v72, v109, v60
	s_waitcnt vmcnt(0)
	v_fmac_f32_e32 v72, v108, v61
	v_cvt_pk_bf16_f32 v1, v72, v72
	v_fma_f32 v73, v111, v59, v107
	v_fmac_f32_e32 v73, v110, v60
	v_fmac_f32_e32 v73, v109, v61
	ds_write_b16 v101, v1 offset:50688
	s_waitcnt lgkmcnt(0)
	v_fmac_f32_e32 v73, v108, v128
	v_cvt_pk_bf16_f32 v1, v73, v73
	v_fma_f32 v70, v111, v60, v107
	v_fmac_f32_e32 v70, v110, v61
	v_fmac_f32_e32 v70, v109, v128
	ds_write_b16 v101, v1 offset:50960
	v_fmac_f32_e32 v70, v108, v129
	v_cvt_pk_bf16_f32 v1, v70, v70
	v_fma_f32 v71, v111, v61, v107
	v_fmac_f32_e32 v71, v110, v128
	v_fmac_f32_e32 v71, v109, v129
	ds_write_b16 v102, v1 offset:50688
	v_fmac_f32_e32 v71, v108, v130
	v_cvt_pk_bf16_f32 v1, v71, v71
	v_fma_f32 v68, v111, v128, v107
	v_fmac_f32_e32 v68, v110, v129
	v_fmac_f32_e32 v68, v109, v130
	ds_write_b16 v101, v1 offset:51504
	v_fmac_f32_e32 v68, v108, v131
	v_cvt_pk_bf16_f32 v1, v68, v68
	v_fma_f32 v69, v111, v129, v107
	v_fmac_f32_e32 v69, v110, v130
	v_fmac_f32_e32 v69, v109, v131
	ds_write_b16 v102, v1 offset:51232
	v_fmac_f32_e32 v69, v108, v132
	v_cvt_pk_bf16_f32 v1, v69, v69
	v_fma_f32 v66, v111, v130, v107
	v_fmac_f32_e32 v66, v110, v131
	v_fmac_f32_e32 v66, v109, v132
	ds_write_b16 v101, v1 offset:52048
	v_fmac_f32_e32 v66, v108, v133
	v_cvt_pk_bf16_f32 v1, v66, v66
	v_fma_f32 v67, v111, v131, v107
	v_fmac_f32_e32 v67, v110, v132
	v_fmac_f32_e32 v67, v109, v133
	ds_write_b16 v102, v1 offset:51776
	v_fmac_f32_e32 v67, v108, v134
	v_cvt_pk_bf16_f32 v1, v67, v67
	v_fma_f32 v64, v111, v132, v107
	v_fmac_f32_e32 v64, v110, v133
	v_fmac_f32_e32 v64, v109, v134
	ds_write_b16 v101, v1 offset:52592
	v_fmac_f32_e32 v64, v108, v135
	v_cvt_pk_bf16_f32 v1, v64, v64
	v_fma_f32 v65, v111, v133, v107
	v_fmac_f32_e32 v65, v110, v134
	v_fmac_f32_e32 v65, v109, v135
	ds_write_b16 v102, v1 offset:52320
	v_fmac_f32_e32 v65, v108, v136
	v_cvt_pk_bf16_f32 v1, v65, v65
	v_fma_f32 v62, v111, v134, v107
	v_fmac_f32_e32 v62, v110, v135
	v_fmac_f32_e32 v62, v109, v136
	ds_write_b16 v101, v1 offset:53136
	v_fmac_f32_e32 v62, v108, v137
	v_cvt_pk_bf16_f32 v1, v62, v62
	v_fma_f32 v63, v111, v135, v107
	v_fmac_f32_e32 v63, v110, v136
	v_fmac_f32_e32 v63, v109, v137
	ds_write_b16 v102, v1 offset:52864
	v_fmac_f32_e32 v63, v108, v138
	v_cvt_pk_bf16_f32 v1, v63, v63
	v_fma_f32 v60, v111, v136, v107
	v_fmac_f32_e32 v60, v110, v137
	v_fmac_f32_e32 v60, v109, v138
	ds_write_b16 v101, v1 offset:53680
	v_fmac_f32_e32 v60, v108, v139
	v_cvt_pk_bf16_f32 v1, v60, v60
	v_fma_f32 v61, v111, v137, v107
	v_fmac_f32_e32 v61, v110, v138
	v_fmac_f32_e32 v61, v109, v139
	ds_write_b16 v102, v1 offset:53408
	v_fmac_f32_e32 v61, v108, v140
	v_cvt_pk_bf16_f32 v1, v61, v61
	v_fma_f32 v58, v111, v138, v107
	v_fmac_f32_e32 v58, v110, v139
	v_fmac_f32_e32 v58, v109, v140
	ds_write_b16 v101, v1 offset:54224
	v_fmac_f32_e32 v58, v108, v141
	v_cvt_pk_bf16_f32 v1, v58, v58
	v_fma_f32 v59, v111, v139, v107
	v_fmac_f32_e32 v59, v110, v140
	v_fmac_f32_e32 v59, v109, v141
	ds_write_b16 v102, v1 offset:53952
	v_fmac_f32_e32 v59, v108, v142
	v_cvt_pk_bf16_f32 v1, v59, v59
	ds_write_b16 v101, v1 offset:54768
	s_waitcnt lgkmcnt(0)
	s_barrier
	ds_read_b128 v[112:115], v103 offset:50688
	ds_read_b128 v[116:119], v103 offset:50752
	s_waitcnt lgkmcnt(1)
	v_mfma_f32_16x16x32_bf16 v[120:123], v[112:115], v[14:17], 0
	v_mfma_f32_16x16x32_bf16 v[112:115], v[112:115], v[30:33], 0
	s_waitcnt lgkmcnt(0)
	v_mfma_f32_16x16x32_bf16 v[120:123], v[116:119], v[18:21], v[120:123]
	v_mfma_f32_16x16x32_bf16 v[112:115], v[116:119], v[34:37], v[112:115]
	ds_read_b128 v[116:119], v103 offset:50816
	ds_read_b128 v[124:127], v103 offset:50880
	s_waitcnt lgkmcnt(1)
	v_mfma_f32_16x16x32_bf16 v[120:123], v[116:119], v[22:25], v[120:123]
	v_mfma_f32_16x16x32_bf16 v[112:115], v[116:119], v[38:41], v[112:115]
	s_waitcnt lgkmcnt(0)
	v_mfma_f32_16x16x32_bf16 v[116:119], v[124:127], v[26:29], v[120:123]
	v_mfma_f32_16x16x32_bf16 v[112:115], v[124:127], v[42:45], v[112:115]
	s_nop 6
	v_fma_f32 v116, -v116, s28, v54
	v_fma_f32 v117, -v117, s28, v54
	v_pk_fma_f32 v[112:113], v[112:113], s[28:29], v[56:57] op_sel:[0,0,1] op_sel_hi:[1,0,1] neg_lo:[1,0,0] neg_hi:[1,0,0]
	v_exp_f32_e32 v116, v116
	v_exp_f32_e32 v117, v117
	v_exp_f32_e32 v112, v112
	v_exp_f32_e32 v113, v113
	v_pk_fma_f32 v[114:115], v[114:115], s[28:29], v[56:57] op_sel:[0,0,1] op_sel_hi:[1,0,1] neg_lo:[1,0,0] neg_hi:[1,0,0]
	v_pk_add_f32 v[116:117], v[116:117], 1.0 op_sel_hi:[1,0]
	v_exp_f32_e32 v114, v114
	v_pk_add_f32 v[112:113], v[112:113], 1.0 op_sel_hi:[1,0]
	v_rcp_f32_e32 v1, v116
	v_rcp_f32_e32 v53, v117
	v_pk_fma_f32 v[116:117], v[118:119], s[28:29], v[54:55] op_sel_hi:[1,0,0] neg_lo:[1,0,0] neg_hi:[1,0,0]
	v_rcp_f32_e32 v112, v112
	v_exp_f32_e32 v116, v116
	v_exp_f32_e32 v117, v117
	v_exp_f32_e32 v115, v115
	ds_write2_b32 v84, v1, v112 offset1:16
	v_rcp_f32_e32 v1, v113
	v_pk_add_f32 v[112:113], v[116:117], 1.0 op_sel_hi:[1,0]
	v_pk_add_f32 v[114:115], v[114:115], 1.0 op_sel_hi:[1,0]
	v_rcp_f32_e32 v112, v112
	v_rcp_f32_e32 v114, v114
	v_rcp_f32_e32 v113, v113
	v_rcp_f32_e32 v115, v115
	ds_write2_b32 v84, v53, v1 offset0:132 offset1:148
	v_add_u32_e32 v1, 0x400, v84
	ds_write2_b32 v1, v112, v114 offset0:8 offset1:24
	ds_write2_b32 v85, v113, v115 offset0:132 offset1:148
	ds_read_b128 v[112:115], v103 offset:55040
	ds_read_b128 v[116:119], v103 offset:55104
	s_waitcnt lgkmcnt(1)
; #define LAS __attribute__((address_space(3)))
; template <int MODE>
; __device__ __forceinline__ void rnn_phase(const RnnP& P, LAS unsigned char* lds, int G, int bid, int nunits) {
;     ...
; #pragma unroll
;         for (int mt = 0; mt < 4; ++mt) { f32x4 d0 = (f32x4){0.f, 0.f, 0.f, 0.f}, d1 = d0;
; #pragma unroll
;             for (int kk = 0; kk < 4; ++kk) { const bf16x8 a = *(const LAS bf16x8*)(XCB + (16 * mt + jj) * 136 + 32 * kk + 8 * q);
;                 d0 = __builtin_amdgcn_mfma_f32_16x16x32_bf16(a, Bf[0][kk], d0, 0, 0, 0); d1 = __builtin_amdgcn_mfma_f32_16x16x32_bf16(a, Bf[1][kk], d1, 0, 0, 0); }
; #pragma unroll
;             for (int ep = 0; ep < 2; ++ep) { const int row = 16 * mt + 4 * q + 2 * ep;
;                 const f32x2 t0 = (f32x2){d0[2 * ep], d0[2 * ep + 1]} * (f32x2){-1.4426950408889634f, -1.4426950408889634f} + (f32x2){nb0, nb0};
;                 const f32x2 t1 = (f32x2){d1[2 * ep], d1[2 * ep + 1]} * (f32x2){-1.4426950408889634f, -1.4426950408889634f} + (f32x2){nb1, nb1};
;                 const f32x2 e0 = (f32x2){__builtin_amdgcn_exp2f(t0.x), __builtin_amdgcn_exp2f(t0.y)} + (f32x2){1.f, 1.f}, e1 = (f32x2){__builtin_amdgcn_exp2f(t1.x), __builtin_amdgcn_exp2f(t1.y)} + (f32x2){1.f, 1.f};
;                 GT[(gate * 64 + row) * GTP + cb + jj] = __builtin_amdgcn_rcpf(e0.x); GT[(gate * 64 + row + 1) * GTP + cb + jj] = __builtin_amdgcn_rcpf(e0.y);
;                 GT[(gate * 64 + row) * GTP + cb + 16 + jj] = __builtin_amdgcn_rcpf(e1.x); GT[(gate * 64 + row + 1) * GTP + cb + 16 + jj] = __builtin_amdgcn_rcpf(e1.y); } }
;         __syncthreads();
	v_mfma_f32_16x16x32_bf16 v[120:123], v[112:115], v[14:17], 0
	v_mfma_f32_16x16x32_bf16 v[112:115], v[112:115], v[30:33], 0
	s_waitcnt lgkmcnt(0)
	v_mfma_f32_16x16x32_bf16 v[120:123], v[116:119], v[18:21], v[120:123]
	v_mfma_f32_16x16x32_bf16 v[112:115], v[116:119], v[34:37], v[112:115]
	ds_read_b128 v[116:119], v103 offset:55168
	ds_read_b128 v[124:127], v103 offset:55232
	s_waitcnt lgkmcnt(1)
	v_mfma_f32_16x16x32_bf16 v[120:123], v[116:119], v[22:25], v[120:123]
	v_mfma_f32_16x16x32_bf16 v[112:115], v[116:119], v[38:41], v[112:115]
	s_waitcnt lgkmcnt(0)
	v_mfma_f32_16x16x32_bf16 v[116:119], v[124:127], v[26:29], v[120:123]
	v_mfma_f32_16x16x32_bf16 v[112:115], v[124:127], v[42:45], v[112:115]
	s_nop 3
	v_add_u32_e32 v120, 0x2000, v84
	s_nop 1
	v_pk_fma_f32 v[116:117], v[116:117], s[28:29], v[54:55] op_sel_hi:[1,0,0] neg_lo:[1,0,0] neg_hi:[1,0,0]
	s_nop 0
	v_exp_f32_e32 v116, v116
	v_exp_f32_e32 v117, v117
	v_pk_fma_f32 v[112:113], v[112:113], s[28:29], v[56:57] op_sel:[0,0,1] op_sel_hi:[1,0,1] neg_lo:[1,0,0] neg_hi:[1,0,0]
	v_pk_fma_f32 v[114:115], v[114:115], s[28:29], v[56:57] op_sel:[0,0,1] op_sel_hi:[1,0,1] neg_lo:[1,0,0] neg_hi:[1,0,0]
	v_exp_f32_e32 v112, v112
	v_exp_f32_e32 v113, v113
	v_pk_add_f32 v[116:117], v[116:117], 1.0 op_sel_hi:[1,0]
	v_exp_f32_e32 v114, v114
	v_rcp_f32_e32 v1, v116
	v_pk_add_f32 v[112:113], v[112:113], 1.0 op_sel_hi:[1,0]
	v_rcp_f32_e32 v53, v117
	v_pk_fma_f32 v[116:117], v[118:119], s[28:29], v[54:55] op_sel_hi:[1,0,0] neg_lo:[1,0,0] neg_hi:[1,0,0]
	v_rcp_f32_e32 v112, v112
	v_exp_f32_e32 v116, v116
	v_exp_f32_e32 v117, v117
	v_exp_f32_e32 v115, v115
	ds_write2_b32 v120, v1, v112 offset0:64 offset1:80
	v_rcp_f32_e32 v1, v113
	v_pk_add_f32 v[112:113], v[116:117], 1.0 op_sel_hi:[1,0]
	v_pk_add_f32 v[114:115], v[114:115], 1.0 op_sel_hi:[1,0]
	v_rcp_f32_e32 v112, v112
	v_rcp_f32_e32 v114, v114
	v_rcp_f32_e32 v113, v113
	v_rcp_f32_e32 v115, v115
	ds_write2_b32 v86, v53, v1 offset0:132 offset1:148
	v_add_u32_e32 v1, 0x2400, v84
	ds_write2_b32 v1, v112, v114 offset0:72 offset1:88
	ds_write2_b32 v87, v113, v115 offset0:132 offset1:148
	ds_read_b128 v[112:115], v103 offset:59392
	ds_read_b128 v[116:119], v103 offset:59456
	s_waitcnt lgkmcnt(1)
	v_mfma_f32_16x16x32_bf16 v[120:123], v[112:115], v[14:17], 0
	v_mfma_f32_16x16x32_bf16 v[112:115], v[112:115], v[30:33], 0
	s_waitcnt lgkmcnt(0)
	v_mfma_f32_16x16x32_bf16 v[120:123], v[116:119], v[18:21], v[120:123]
	v_mfma_f32_16x16x32_bf16 v[112:115], v[116:119], v[34:37], v[112:115]
	ds_read_b128 v[116:119], v103 offset:59520
	ds_read_b128 v[124:127], v103 offset:59584
	s_waitcnt lgkmcnt(1)
	v_mfma_f32_16x16x32_bf16 v[120:123], v[116:119], v[22:25], v[120:123]
	v_mfma_f32_16x16x32_bf16 v[112:115], v[116:119], v[38:41], v[112:115]
	s_waitcnt lgkmcnt(0)
	v_mfma_f32_16x16x32_bf16 v[116:119], v[124:127], v[26:29], v[120:123]
	v_mfma_f32_16x16x32_bf16 v[112:115], v[124:127], v[42:45], v[112:115]
	s_nop 3
	v_add_u32_e32 v120, 0x4000, v84
	s_nop 1
	v_pk_fma_f32 v[116:117], v[116:117], s[28:29], v[54:55] op_sel_hi:[1,0,0] neg_lo:[1,0,0] neg_hi:[1,0,0]
	s_nop 0
	v_exp_f32_e32 v116, v116
	v_exp_f32_e32 v117, v117
	v_pk_fma_f32 v[112:113], v[112:113], s[28:29], v[56:57] op_sel:[0,0,1] op_sel_hi:[1,0,1] neg_lo:[1,0,0] neg_hi:[1,0,0]
	v_pk_fma_f32 v[114:115], v[114:115], s[28:29], v[56:57] op_sel:[0,0,1] op_sel_hi:[1,0,1] neg_lo:[1,0,0] neg_hi:[1,0,0]
	v_exp_f32_e32 v112, v112
	v_exp_f32_e32 v113, v113
	v_pk_add_f32 v[116:117], v[116:117], 1.0 op_sel_hi:[1,0]
	v_exp_f32_e32 v114, v114
	v_rcp_f32_e32 v1, v116
	v_pk_add_f32 v[112:113], v[112:113], 1.0 op_sel_hi:[1,0]
	v_rcp_f32_e32 v53, v117
	v_pk_fma_f32 v[116:117], v[118:119], s[28:29], v[54:55] op_sel_hi:[1,0,0] neg_lo:[1,0,0] neg_hi:[1,0,0]
	v_rcp_f32_e32 v112, v112
	v_exp_f32_e32 v116, v116
	v_exp_f32_e32 v117, v117
	v_exp_f32_e32 v115, v115
	ds_write2_b32 v120, v1, v112 offset0:128 offset1:144
	v_rcp_f32_e32 v1, v113
	v_pk_add_f32 v[112:113], v[116:117], 1.0 op_sel_hi:[1,0]
	v_pk_add_f32 v[114:115], v[114:115], 1.0 op_sel_hi:[1,0]
	v_rcp_f32_e32 v112, v112
	v_rcp_f32_e32 v114, v114
	v_rcp_f32_e32 v113, v113
	v_rcp_f32_e32 v115, v115
	ds_write2_b32 v88, v53, v1 offset0:132 offset1:148
	v_add_u32_e32 v1, 0x4400, v84
	ds_write2_b32 v1, v112, v114 offset0:136 offset1:152
	ds_write2_b32 v89, v113, v115 offset0:132 offset1:148
	ds_read_b128 v[112:115], v103 offset:63744
	ds_read_b128 v[116:119], v103 offset:63808
	s_waitcnt lgkmcnt(1)
	v_mfma_f32_16x16x32_bf16 v[120:123], v[112:115], v[14:17], 0
	v_mfma_f32_16x16x32_bf16 v[112:115], v[112:115], v[30:33], 0
	s_waitcnt lgkmcnt(0)
	v_mfma_f32_16x16x32_bf16 v[120:123], v[116:119], v[18:21], v[120:123]
	v_mfma_f32_16x16x32_bf16 v[112:115], v[116:119], v[34:37], v[112:115]
	ds_read_b128 v[116:119], v103 offset:63872
	ds_read_b128 v[124:127], v103 offset:63936
	s_waitcnt lgkmcnt(1)
	v_mfma_f32_16x16x32_bf16 v[120:123], v[116:119], v[22:25], v[120:123]
	v_mfma_f32_16x16x32_bf16 v[112:115], v[116:119], v[38:41], v[112:115]
	s_waitcnt lgkmcnt(0)
	v_mfma_f32_16x16x32_bf16 v[116:119], v[124:127], v[26:29], v[120:123]
	v_mfma_f32_16x16x32_bf16 v[112:115], v[124:127], v[42:45], v[112:115]
	s_nop 3
	v_add_u32_e32 v120, 0x6000, v84
	s_nop 1
	v_pk_fma_f32 v[116:117], v[116:117], s[28:29], v[54:55] op_sel_hi:[1,0,0] neg_lo:[1,0,0] neg_hi:[1,0,0]
	s_nop 0
	v_exp_f32_e32 v116, v116
	v_exp_f32_e32 v117, v117
	v_pk_fma_f32 v[112:113], v[112:113], s[28:29], v[56:57] op_sel:[0,0,1] op_sel_hi:[1,0,1] neg_lo:[1,0,0] neg_hi:[1,0,0]
	v_pk_fma_f32 v[114:115], v[114:115], s[28:29], v[56:57] op_sel:[0,0,1] op_sel_hi:[1,0,1] neg_lo:[1,0,0] neg_hi:[1,0,0]
	v_exp_f32_e32 v112, v112
	v_exp_f32_e32 v113, v113
	v_pk_add_f32 v[116:117], v[116:117], 1.0 op_sel_hi:[1,0]
	v_exp_f32_e32 v114, v114
	v_rcp_f32_e32 v1, v116
	v_pk_add_f32 v[112:113], v[112:113], 1.0 op_sel_hi:[1,0]
	v_rcp_f32_e32 v53, v117
	v_pk_fma_f32 v[116:117], v[118:119], s[28:29], v[54:55] op_sel_hi:[1,0,0] neg_lo:[1,0,0] neg_hi:[1,0,0]
	v_rcp_f32_e32 v112, v112
	v_exp_f32_e32 v116, v116
	v_exp_f32_e32 v117, v117
	v_exp_f32_e32 v115, v115
	ds_write2_b32 v120, v1, v112 offset0:192 offset1:208
	v_rcp_f32_e32 v1, v113
	v_pk_add_f32 v[112:113], v[116:117], 1.0 op_sel_hi:[1,0]
	v_pk_add_f32 v[114:115], v[114:115], 1.0 op_sel_hi:[1,0]
	v_rcp_f32_e32 v112, v112
	v_rcp_f32_e32 v114, v114
	v_rcp_f32_e32 v113, v113
	v_rcp_f32_e32 v115, v115
	ds_write2_b32 v90, v53, v1 offset0:132 offset1:148
	v_add_u32_e32 v1, 0x6400, v84
	ds_write2_b32 v1, v112, v114 offset0:200 offset1:216
	ds_write2_b32 v91, v113, v115 offset0:132 offset1:148
	s_waitcnt lgkmcnt(0)
	s_barrier
; template <int MODE>
; __device__ __forceinline__ void rnn_phase(const RnnP& P, LAS unsigned char* lds, int G, int bid, int nunits) {
;     ...
;         float Lr[16], Pr[16];
;         { float L = 0.f, Pp = 1.f;
; #pragma unroll
;           for (int ip = 0; ip < 8; ++ip) { const int i = 2 * ip;
;               const f32x2 r2 = (f32x2){GT[(16 * rg + i) * GTP + ch], GT[(16 * rg + i + 1) * GTP + ch]}, ig2 = (f32x2){GT[(64 + 16 * rg + i) * GTP + ch], GT[(64 + 16 * rg + i + 1) * GTP + ch]};
;               const f32x2 t2 = r2 * (f32x2){c2s, c2s};
;               const f32x2 a2 = (f32x2){__builtin_amdgcn_exp2f(t2.x), __builtin_amdgcn_exp2f(t2.y)};
;               const f32x2 om2 = (f32x2){1.f, 1.f} - a2 * a2;
;               const f32x2 bt2 = (f32x2){__builtin_amdgcn_sqrtf(om2.x), __builtin_amdgcn_sqrtf(om2.y)} * (ig2 * (f32x2){xc[i], xc[i + 1]});
;               L = a2.x * L + bt2.x; Pp *= a2.x; Lr[i] = L; Pr[i] = Pp;
;               L = a2.y * L + bt2.y; Pp *= a2.y; Lr[i + 1] = L; Pr[i + 1] = Pp; } }
;         if (MODE == 0) {
;             CAR[rg * 128 + ch] = Pr[15]; CAR[512 + rg * 128 + ch] = Lr[15];
;             __syncthreads();
;             if (rg == 0) { float Pt = 1.f, Lt = 0.f;
; #pragma unroll
;                 for (int g = 0; g < 4; ++g) { const float pg = CAR[g * 128 + ch], lg = CAR[512 + g * 128 + ch]; Lt = pg * Lt + lg; Pt *= pg; }
;                 P.PE[(size_t)c * 2048 + chg] = Pt; P.LE[(size_t)c * 2048 + chg] = Lt; }
	ds_read2_b32 v[112:113], v92 offset1:132
	v_add_u32_e32 v1, 0x8400, v92
	ds_read2_b32 v[114:115], v1 offset1:132
	ds_read2_b32 v[118:119], v93 offset1:132
	s_waitcnt lgkmcnt(2)
	v_pk_mul_f32 v[112:113], v[56:57], v[112:113] op_sel_hi:[0,1]
	v_exp_f32_e32 v112, v112
	v_exp_f32_e32 v113, v113
	s_waitcnt lgkmcnt(1)
	v_pk_mul_f32 v[72:73], v[72:73], v[114:115]
	s_waitcnt lgkmcnt(0)
	v_pk_mul_f32 v[114:115], v[56:57], v[118:119] op_sel_hi:[0,1]
	v_exp_f32_e32 v114, v114
	v_pk_fma_f32 v[116:117], v[112:113], v[112:113], 1.0 op_sel_hi:[1,1,0] neg_lo:[1,0,0] neg_hi:[1,0,0]
	v_exp_f32_e32 v115, v115
	v_sqrt_f32_e32 v116, v116
	v_sqrt_f32_e32 v117, v117
	v_pk_fma_f32 v[118:119], v[114:115], v[114:115], 1.0 op_sel_hi:[1,1,0] neg_lo:[1,0,0] neg_hi:[1,0,0]
	s_nop 0
	v_sqrt_f32_e32 v118, v118
	v_pk_mul_f32 v[72:73], v[72:73], v[116:117]
	v_sqrt_f32_e32 v119, v119
	v_fma_f32 v1, 0, v112, v72
	v_fmac_f32_e32 v73, v113, v1
	v_add_u32_e32 v1, 0x8800, v92
	ds_read2_b32 v[116:117], v1 offset0:8 offset1:140
	v_mul_f32_e32 v1, v113, v112
	ds_read2_b32 v[112:113], v94 offset1:132
	v_mul_f32_e32 v1, v1, v114
	v_mul_f32_e32 v1, v115, v1
	s_waitcnt lgkmcnt(1)
	v_pk_mul_f32 v[70:71], v[70:71], v[116:117]
	s_nop 0
	v_pk_mul_f32 v[70:71], v[70:71], v[118:119]
	s_nop 0
	v_fma_f32 v53, v114, v73, v70
	s_waitcnt lgkmcnt(0)
	v_pk_mul_f32 v[72:73], v[56:57], v[112:113] op_sel_hi:[0,1]
	v_exp_f32_e32 v72, v72
	v_exp_f32_e32 v73, v73
	v_fmac_f32_e32 v71, v115, v53
	v_add_u32_e32 v53, 0x8c00, v92
	ds_read2_b32 v[112:113], v53 offset0:16 offset1:148
	v_pk_fma_f32 v[116:117], v[72:73], v[72:73], 1.0 op_sel_hi:[1,1,0] neg_lo:[1,0,0] neg_hi:[1,0,0]
	ds_read2_b32 v[114:115], v95 offset1:132
	v_sqrt_f32_e32 v116, v116
	v_sqrt_f32_e32 v117, v117
	s_waitcnt lgkmcnt(1)
	v_pk_mul_f32 v[68:69], v[68:69], v[112:113]
	v_mul_f32_e32 v1, v1, v72
	v_mul_f32_e32 v1, v73, v1
	v_pk_mul_f32 v[68:69], v[68:69], v[116:117]
	s_nop 0
	v_fma_f32 v53, v72, v71, v68
	s_waitcnt lgkmcnt(0)
	v_pk_mul_f32 v[70:71], v[56:57], v[114:115] op_sel_hi:[0,1]
	v_exp_f32_e32 v70, v70
	v_exp_f32_e32 v71, v71
	v_fmac_f32_e32 v69, v73, v53
	v_add_u32_e32 v53, 0x9000, v92
	ds_read2_b32 v[112:113], v53 offset0:24 offset1:156
	v_pk_fma_f32 v[114:115], v[70:71], v[70:71], 1.0 op_sel_hi:[1,1,0] neg_lo:[1,0,0] neg_hi:[1,0,0]
	ds_read2_b32 v[72:73], v96 offset1:132
	v_sqrt_f32_e32 v114, v114
	v_sqrt_f32_e32 v115, v115
	s_waitcnt lgkmcnt(1)
	v_pk_mul_f32 v[66:67], v[66:67], v[112:113]
	v_mul_f32_e32 v1, v1, v70
	v_mul_f32_e32 v1, v71, v1
	v_pk_mul_f32 v[66:67], v[66:67], v[114:115]
	s_nop 0
	v_fma_f32 v53, v70, v69, v66
	s_waitcnt lgkmcnt(0)
	v_pk_mul_f32 v[68:69], v[56:57], v[72:73] op_sel_hi:[0,1]
	v_exp_f32_e32 v68, v68
	v_exp_f32_e32 v69, v69
	v_fmac_f32_e32 v67, v71, v53
	v_add_u32_e32 v53, 0x9400, v92
	ds_read2_b32 v[72:73], v53 offset0:32 offset1:164
	v_pk_fma_f32 v[112:113], v[68:69], v[68:69], 1.0 op_sel_hi:[1,1,0] neg_lo:[1,0,0] neg_hi:[1,0,0]
	ds_read2_b32 v[70:71], v97 offset1:132
	v_sqrt_f32_e32 v112, v112
	v_sqrt_f32_e32 v113, v113
	s_waitcnt lgkmcnt(1)
	v_pk_mul_f32 v[64:65], v[64:65], v[72:73]
	v_mul_f32_e32 v1, v1, v68
	v_mul_f32_e32 v1, v69, v1
	v_pk_mul_f32 v[64:65], v[64:65], v[112:113]
	s_nop 0
	v_fma_f32 v53, v68, v67, v64
	s_waitcnt lgkmcnt(0)
	v_pk_mul_f32 v[66:67], v[56:57], v[70:71] op_sel_hi:[0,1]
	v_exp_f32_e32 v66, v66
	v_exp_f32_e32 v67, v67
	v_fmac_f32_e32 v65, v69, v53
	v_add_u32_e32 v53, 0x9800, v92
	ds_read2_b32 v[70:71], v53 offset0:40 offset1:172
	v_pk_fma_f32 v[72:73], v[66:67], v[66:67], 1.0 op_sel_hi:[1,1,0] neg_lo:[1,0,0] neg_hi:[1,0,0]
	ds_read2_b32 v[68:69], v98 offset1:132
	v_sqrt_f32_e32 v72, v72
	v_sqrt_f32_e32 v73, v73
	s_waitcnt lgkmcnt(1)
	v_pk_mul_f32 v[62:63], v[62:63], v[70:71]
	v_mul_f32_e32 v1, v1, v66
	v_mul_f32_e32 v1, v67, v1
	v_pk_mul_f32 v[62:63], v[62:63], v[72:73]
	ds_read2_b32 v[72:73], v99 offset1:132
	v_fma_f32 v53, v66, v65, v62
	s_waitcnt lgkmcnt(1)
	v_pk_mul_f32 v[64:65], v[56:57], v[68:69] op_sel_hi:[0,1]
	v_exp_f32_e32 v64, v64
	v_exp_f32_e32 v65, v65
	v_fmac_f32_e32 v63, v67, v53
	v_add_u32_e32 v53, 0x9c00, v92
	ds_read2_b32 v[68:69], v53 offset0:48 offset1:180
	v_pk_fma_f32 v[70:71], v[64:65], v[64:65], 1.0 op_sel_hi:[1,1,0] neg_lo:[1,0,0] neg_hi:[1,0,0]
	v_mul_f32_e32 v1, v1, v64
	v_sqrt_f32_e32 v70, v70
	v_sqrt_f32_e32 v71, v71
	s_waitcnt lgkmcnt(0)
	v_pk_mul_f32 v[60:61], v[60:61], v[68:69]
	v_mul_f32_e32 v1, v65, v1
	v_pk_mul_f32 v[60:61], v[60:61], v[70:71]
	s_nop 0
	v_fma_f32 v53, v64, v63, v60
	v_pk_mul_f32 v[62:63], v[56:57], v[72:73] op_sel_hi:[0,1]
	v_exp_f32_e32 v62, v62
	v_exp_f32_e32 v63, v63
	v_add_u32_e32 v60, 0xa000, v92
	ds_read2_b32 v[66:67], v60 offset0:56 offset1:188
	v_fmac_f32_e32 v61, v65, v53
	v_pk_fma_f32 v[68:69], v[62:63], v[62:63], 1.0 op_sel_hi:[1,1,0] neg_lo:[1,0,0] neg_hi:[1,0,0]
	v_mul_f32_e32 v1, v1, v62
	v_sqrt_f32_e32 v68, v68
	v_sqrt_f32_e32 v69, v69
	s_waitcnt lgkmcnt(0)
	v_pk_mul_f32 v[58:59], v[58:59], v[66:67]
	v_mul_f32_e32 v1, v63, v1
	v_pk_mul_f32 v[58:59], v[58:59], v[68:69]
	s_nop 0
	v_fma_f32 v53, v62, v61, v58
	v_fmac_f32_e32 v59, v63, v53
	ds_write_b32 v79, v1
	ds_write_b32 v80, v59 offset:2048
	s_waitcnt lgkmcnt(0)
	s_barrier
	s_and_saveexec_b64 s[40:41], s[18:19]
	s_cbranch_execz .LBB0_1197
	ds_read2st64_b32 v[58:59], v79 offset1:2
	ds_read2st64_b32 v[60:61], v79 offset0:8 offset1:10
	ds_read2st64_b32 v[62:63], v79 offset0:4 offset1:6
	ds_read2st64_b32 v[64:65], v79 offset0:12 offset1:14
	s_ashr_i32 s37, s36, 31
	s_lshl_b64 s[36:37], s[36:37], 13
	s_add_u32 s42, s0, s36
	s_waitcnt lgkmcnt(2)
	v_fma_f32 v1, 0, v58, v60
	s_addc_u32 s43, s1, s37
	v_mul_f32_e32 v53, v58, v59
	v_fmac_f32_e32 v61, v1, v59
	s_add_u32 s36, s44, s36
	s_waitcnt lgkmcnt(0)
	v_fma_f32 v1, v61, v62, v64
	v_mul_f32_e32 v53, v53, v62
	v_lshlrev_b64 v[58:59], 2, v[46:47]
	s_addc_u32 s37, s45, s37
	v_fmac_f32_e32 v65, v1, v63
	v_mul_f32_e32 v1, v53, v63
	v_lshl_add_u64 v[60:61], s[42:43], 0, v[58:59]
	v_lshl_add_u64 v[58:59], s[36:37], 0, v[58:59]
	global_store_dword v[60:61], v1, off
	global_store_dword v[58:59], v65, off
	s_branch .LBB0_1197

; #define GAS __attribute__((address_space(1)))
; template <int MODE>
; __device__ __forceinline__ void rnn_phase(const RnnP& P, LAS unsigned char* lds, int G, int bid, int nunits) {
;     ...
;         const int chg = n * 128 + ch;
;         if (n != n_loaded) {
;             const bf16* WT = (gate ? P.WXT : P.WAT) + (size_t)n * 16384;
; #pragma unroll
;             for (int nt = 0; nt < 2; ++nt)
; #pragma unroll
;                 for (int kk = 0; kk < 4; ++kk) Bf[nt][kk] = *(const GAS bf16x8*)(WT + (size_t)(cb + 16 * nt + jj) * 128 + 32 * kk + 8 * q);
;             const float* bsrc = (gate ? P.b_x : P.b_a) + n * 128 + cb; nb0 = -1.4426950408889634f * bsrc[jj]; nb1 = -1.4426950408889634f * bsrc[16 + jj];
;             w0 = P.wconv[chg]; w1 = P.wconv[2048 + chg]; w2 = P.wconv[4096 + chg]; w3 = P.wconv[6144 + chg]; bc = P.bconv[chg];
;             c2s = -1.4426950408889634f * 8.f * log1pf(__expf(-P.lam[chg])); n_loaded = n; }
.LBB0_2305:
	s_mov_b32 s40, s82
	s_lshl_b32 s88, s4, 7
	s_mov_b32 s82, s4
	s_cmp_eq_u32 s4, s40
	v_or_b32_e32 v64, s88, v123
	s_cbranch_scc1 .LBB0_2307
	v_mov_b32_e32 v65, v10
	v_lshlrev_b64 v[40:41], 2, v[64:65]
	v_lshl_add_u64 v[24:25], s[46:47], 0, v[40:41]
	global_load_dword v1, v[24:25], off
	s_mov_b32 s89, s67
	v_lshl_add_u64 v[42:43], s[88:89], 2, v[60:61]
	global_load_dword v11, v[42:43], off
	s_lshl_b32 s66, s82, 15
	v_lshl_add_u64 v[44:45], v[58:59], 0, s[66:67]
	v_add_co_u32_e32 v52, vcc, 0x1000, v44
	s_movk_i32 s4, 0x2000
	v_lshl_add_u64 v[70:71], s[52:53], 0, v[40:41]
	v_addc_co_u32_e32 v53, vcc, 0, v45, vcc
	v_add_co_u32_e32 v72, vcc, s4, v70
	s_movk_i32 s40, 0x4000
	s_nop 0
	v_addc_co_u32_e32 v73, vcc, 0, v71, vcc
	v_add_co_u32_e32 v74, vcc, s40, v70
	s_movk_i32 s41, 0x6000
	v_lshl_add_u64 v[40:41], s[54:55], 0, v[40:41]
	v_addc_co_u32_e32 v75, vcc, 0, v71, vcc
	global_load_dwordx4 v[24:27], v[44:45], off
	global_load_dwordx4 v[28:31], v[44:45], off offset:64
	global_load_dwordx4 v[32:35], v[44:45], off offset:128
	global_load_dwordx4 v[36:39], v[44:45], off offset:192
	global_load_dword v69, v[42:43], off offset:64
	v_add_co_u32_e32 v76, vcc, s41, v70
	global_load_dword v164, v[40:41], off
	s_nop 0
	global_load_dwordx4 v[40:43], v[52:53], off
	global_load_dwordx4 v[44:47], v[52:53], off offset:64
	global_load_dwordx4 v[48:51], v[52:53], off offset:128
	s_nop 0
	global_load_dwordx4 v[52:55], v[52:53], off offset:192
	v_addc_co_u32_e32 v77, vcc, 0, v71, vcc
	global_load_dword v168, v[70:71], off
	global_load_dword v167, v[72:73], off
	global_load_dword v166, v[74:75], off
	global_load_dword v165, v[76:77], off
	s_mov_b32 s42, 0x3f2aaaab
	s_mov_b32 s43, 0x3f317218
	s_mov_b32 s4, 0x7f800000
	s_waitcnt vmcnt(15)
	v_mul_f32_e32 v1, 0xbfb8aa3b, v1
	v_exp_f32_e32 v1, v1
	s_waitcnt vmcnt(14)
	v_mul_f32_e32 v66, 0xbfb8aa3b, v11
	v_add_f32_e32 v11, 1.0, v1
	v_add_f32_e32 v57, -1.0, v11
	v_frexp_mant_f32_e32 v63, v11
	v_cvt_f64_f32_e32 v[70:71], v11
	v_sub_f32_e32 v65, v57, v11
	v_frexp_exp_i32_f64_e32 v68, v[70:71]
	v_cmp_gt_f32_e32 vcc, s42, v63
	v_sub_f32_e32 v57, v1, v57
	v_add_f32_e32 v65, 1.0, v65
	v_subbrev_co_u32_e32 v63, vcc, 0, v68, vcc
	v_add_f32_e32 v57, v57, v65
	v_sub_u32_e32 v65, 0, v63
	v_ldexp_f32 v11, v11, v65
	v_cvt_f32_i32_e32 v70, v63
	v_ldexp_f32 v57, v57, v65
	v_add_f32_e32 v63, -1.0, v11
	v_add_f32_e32 v65, 1.0, v11
	v_add_f32_e32 v68, 1.0, v63
	v_add_f32_e32 v71, -1.0, v65
	v_sub_f32_e32 v68, v11, v68
	v_sub_f32_e32 v11, v11, v71
	v_add_f32_e32 v11, v57, v11
	v_add_f32_e32 v68, v57, v68
	v_add_f32_e32 v57, v65, v11
	v_rcp_f32_e32 v71, v57
	v_add_f32_e32 v73, v63, v68
	v_sub_f32_e32 v65, v57, v65
	v_sub_f32_e32 v11, v11, v65
	v_mul_f32_e32 v65, v73, v71
	v_mul_f32_e32 v74, v57, v65
	v_fma_f32 v76, v65, v57, -v74
	v_fmac_f32_e32 v76, v65, v11
	v_add_f32_e32 v72, v74, v76
	v_sub_f32_e32 v75, v73, v72
	v_sub_f32_e32 v63, v73, v63
	v_mov_b32_e32 v77, v72
	v_pk_add_f32 v[72:73], v[72:73], v[74:75] neg_lo:[0,1] neg_hi:[0,1]
	v_sub_f32_e32 v63, v68, v63
	v_pk_add_f32 v[72:73], v[72:73], v[76:77] neg_lo:[0,1] neg_hi:[0,1]
	v_cmp_neq_f32_e32 vcc, s4, v1
	v_add_f32_e32 v63, v63, v73
	v_add_f32_e32 v63, v72, v63
	v_add_f32_e32 v73, v75, v63
	v_mul_f32_e32 v68, v71, v73
	v_mul_f32_e32 v74, v57, v68
	v_fma_f32 v76, v68, v57, -v74
	v_sub_f32_e32 v72, v75, v73
	v_fmac_f32_e32 v76, v68, v11
	v_add_f32_e32 v63, v63, v72
	v_add_f32_e32 v72, v74, v76
	v_sub_f32_e32 v75, v73, v72
	v_add_f32_e32 v78, v65, v68
	v_mov_b32_e32 v77, v72
	v_pk_add_f32 v[72:73], v[72:73], v[74:75] neg_lo:[0,1] neg_hi:[0,1]
	v_sub_f32_e32 v57, v78, v65
	v_pk_add_f32 v[72:73], v[72:73], v[76:77] neg_lo:[0,1] neg_hi:[0,1]
	v_sub_f32_e32 v11, v68, v57
	v_add_f32_e32 v57, v63, v73
	v_add_f32_e32 v57, v72, v57
	v_add_f32_e32 v57, v75, v57
	v_mul_f32_e32 v57, v71, v57
	v_add_f32_e32 v11, v11, v57
	v_add_f32_e32 v57, v78, v11
	v_mul_f32_e32 v63, v57, v57
	v_fmamk_f32 v68, v63, 0x3e9b6dac, v150
	v_mul_f32_e32 v71, v57, v63
	v_fmaak_f32 v63, v63, v68, 0x3f2aaada
	v_pk_mul_f32 v[74:75], v[70:71], v[62:63]
	v_ldexp_f32 v73, v57, 1
	v_fma_f32 v72, v70, s43, -v74
	v_fmac_f32_e32 v72, 0xb102e308, v70
	v_sub_f32_e32 v65, v57, v78
	v_pk_add_f32 v[70:71], v[74:75], v[72:73]
	v_sub_f32_e32 v11, v11, v65
	v_sub_f32_e32 v57, v71, v73
	v_ldexp_f32 v11, v11, 1
	v_sub_f32_e32 v57, v75, v57
	v_mov_b32_e32 v76, v74
	v_add_f32_e32 v77, v11, v57
	v_pk_add_f32 v[78:79], v[70:71], v[74:75] neg_lo:[0,1] neg_hi:[0,1]
	v_pk_add_f32 v[74:75], v[70:71], v[76:77]
	v_mov_b32_e32 v73, v70
	v_mov_b32_e32 v79, v75
	v_pk_add_f32 v[82:83], v[72:73], v[78:79] neg_lo:[0,1] neg_hi:[0,1]
	v_pk_add_f32 v[72:73], v[72:73], v[78:79]
	v_mov_b32_e32 v81, v70
	v_pk_add_f32 v[78:79], v[72:73], v[70:71] op_sel:[1,0] op_sel_hi:[0,1] neg_lo:[0,1] neg_hi:[0,1]
	v_mov_b32_e32 v80, v77
	v_mov_b32_e32 v76, v75
	v_mov_b32_e32 v77, v73
	v_pk_mov_b32 v[70:71], v[70:71], v[78:79] op_sel:[1,0]
	v_pk_add_f32 v[74:75], v[74:75], v[78:79] op_sel_hi:[1,0] neg_lo:[0,1] neg_hi:[0,1]
	v_pk_add_f32 v[70:71], v[76:77], v[70:71] neg_lo:[0,1] neg_hi:[0,1]
	v_mov_b32_e32 v74, v82
	v_pk_add_f32 v[70:71], v[80:81], v[70:71] neg_lo:[0,1] neg_hi:[0,1]
	v_mov_b32_e32 v83, v73
	v_pk_add_f32 v[74:75], v[74:75], v[70:71]
	s_mov_b32 s4, 0x33800000
	v_pk_add_f32 v[76:77], v[74:75], v[74:75] op_sel:[0,1] op_sel_hi:[1,0]
	s_nop 0
	v_pk_add_f32 v[72:73], v[72:73], v[76:77] op_sel:[1,0] op_sel_hi:[0,1]
	v_mov_b32_e32 v75, v72
	v_mov_b32_e32 v71, v76
	v_pk_add_f32 v[76:77], v[74:75], v[82:83] neg_lo:[0,1] neg_hi:[0,1]
	s_nop 0
	v_sub_f32_e32 v11, v74, v76
	v_pk_add_f32 v[70:71], v[70:71], v[76:77] neg_lo:[0,1] neg_hi:[0,1]
	v_sub_f32_e32 v11, v82, v11
	v_add_f32_e32 v11, v70, v11
	v_add_f32_e32 v11, v11, v71
	v_add_f32_e32 v11, v72, v11
	v_cndmask_b32_e32 v11, v159, v11, vcc
	v_cmp_ngt_f32_e32 vcc, -1.0, v1
	s_nop 1
	v_cndmask_b32_e32 v11, v160, v11, vcc
	v_cmp_neq_f32_e32 vcc, -1.0, v1
	s_nop 1
	v_cndmask_b32_e32 v11, v161, v11, vcc
	v_cmp_lt_f32_e64 vcc, |v1|, s4
	s_nop 1
	v_cndmask_b32_e32 v68, v11, v1, vcc
	s_waitcnt vmcnt(0)
	v_pk_mul_f32 v[68:69], v[68:69], s[80:81]

; #define LAS __attribute__((address_space(3)))
; template <int MODE>
; __device__ __forceinline__ void rnn_phase(const RnnP& P, LAS unsigned char* lds, int G, int bid, int nunits) {
;     ...
;         for (int k = 0; k < 3; ++k) { const int i = tid + k * NTHR; if (i < 67 * 16) { const int j = i >> 4, cc = i & 15; const v4u v = pre.x[k]; f32x4 a, b;
;             a.x = __builtin_bit_cast(float, v.x << 16); a.y = __builtin_bit_cast(float, v.x & 0xffff0000u); a.z = __builtin_bit_cast(float, v.y << 16); a.w = __builtin_bit_cast(float, v.y & 0xffff0000u);
;             b.x = __builtin_bit_cast(float, v.z << 16); b.y = __builtin_bit_cast(float, v.z & 0xffff0000u); b.z = __builtin_bit_cast(float, v.w << 16); b.w = __builtin_bit_cast(float, v.w & 0xffff0000u);
;             *(LAS f32x4*)(XRF + j * 128 + cc * 8) = a; *(LAS f32x4*)(XRF + j * 128 + cc * 8 + 4) = b; } }
.LBB0_2309:
	v_lshlrev_b32_e32 v70, 16, v2
	v_and_b32_e32 v71, 0xffff0000, v2
	v_lshlrev_b32_e32 v72, 16, v3
	v_and_b32_e32 v73, 0xffff0000, v3
	v_lshlrev_b32_e32 v74, 16, v4
	v_and_b32_e32 v75, 0xffff0000, v4
	v_lshlrev_b32_e32 v76, 16, v5
	v_and_b32_e32 v77, 0xffff0000, v5
	ds_write_b128 v129, v[70:73]
	ds_write_b128 v129, v[74:77] offset:16
	s_or_b64 exec, exec, s[40:41]
	s_and_saveexec_b64 s[40:41], s[8:9]
	s_cbranch_execnz .LBB0_2350

; #define LAS __attribute__((address_space(3)))
; template <int MODE>
; __device__ __forceinline__ void rnn_phase(const RnnP& P, LAS unsigned char* lds, int G, int bid, int nunits) {
;     ...
;         for (int k = 0; k < 3; ++k) { const int i = tid + k * NTHR; if (i < 67 * 16) { const int j = i >> 4, cc = i & 15; const v4u v = pre.x[k]; f32x4 a, b;
;             a.x = __builtin_bit_cast(float, v.x << 16); a.y = __builtin_bit_cast(float, v.x & 0xffff0000u); a.z = __builtin_bit_cast(float, v.y << 16); a.w = __builtin_bit_cast(float, v.y & 0xffff0000u);
;             b.x = __builtin_bit_cast(float, v.z << 16); b.y = __builtin_bit_cast(float, v.z & 0xffff0000u); b.z = __builtin_bit_cast(float, v.w << 16); b.w = __builtin_bit_cast(float, v.w & 0xffff0000u);
;             *(LAS f32x4*)(XRF + j * 128 + cc * 8) = a; *(LAS f32x4*)(XRF + j * 128 + cc * 8 + 4) = b; } }
;         if (MODE == 1) {
; #pragma unroll
;             for (int k = 0; k < 2; ++k) { const int i = tid + k * NTHR, j = i >> 4, cc = i & 15; *(LAS v4u*)(YGS + j * 128 + cc * 8) = pre.y[k]; } }
;         const int un = u + G; const bool has_next = un < nunits;
;         int R0n = R0, nn = n, sampn = samp, cn = c;
;         if (has_next) { rnn_decode<MODE>(un, R0n, nn, sampn, cn); rnn_issue<MODE>(P, pre, tid, R0n, nn, sampn, cn); }
.LBB0_2311:
	v_lshlrev_b32_e32 v70, 16, v12
	v_and_b32_e32 v71, 0xffff0000, v12
	v_lshlrev_b32_e32 v72, 16, v13
	v_and_b32_e32 v73, 0xffff0000, v13
	v_lshlrev_b32_e32 v74, 16, v14
	v_and_b32_e32 v75, 0xffff0000, v14
	v_lshlrev_b32_e32 v76, 16, v15
	v_and_b32_e32 v77, 0xffff0000, v15
	ds_write_b128 v131, v[70:73]
	ds_write_b128 v131, v[74:77] offset:16
.LBB0_2312:
	s_or_b64 exec, exec, s[40:41]
	s_add_i32 s61, s61, s33
	s_cmpk_gt_i32 s61, 0x104f
	s_cselect_b64 s[90:91], -1, 0
	s_and_b64 vcc, exec, s[90:91]
	s_mov_b32 s63, s70
	s_mov_b32 s4, s82
	s_mov_b32 s62, s0
	ds_write_b128 v132, v[16:19] offset:34304
	ds_write_b128 v132, v[20:23] offset:42496
	s_cbranch_vccnz .LBB0_2324
	s_cmp_gt_i32 s61, 63
	s_cselect_b64 s[40:41], -1, 0
	s_mov_b64 s[92:93], -1
	s_and_b64 vcc, exec, s[40:41]
	s_cbranch_vccnz .LBB0_2315
	s_and_b32 s62, s5, 0xffffffc0
	s_mov_b64 s[92:93], 0

; __device__ __forceinline__ unsigned cvt_pk_bf16(float lo, float hi) { unsigned r; asm volatile("v_cvt_pk_bf16_f32 %0, %1, %2" : "=v"(r) : "v"(lo), "v"(hi)); return r; }
; #define LAS __attribute__((address_space(3)))
; template <int MODE>
; __device__ __forceinline__ void rnn_phase(const RnnP& P, LAS unsigned char* lds, int G, int bid, int nunits) {
;     ...
;         { float x3, x2, x1;
;           if (samp) { const float* sc = P.st_conv + (size_t)((R0 >> 4) + rg) * 3 * 2048 + chg; x3 = sc[0]; x2 = sc[2048]; x1 = sc[4096]; }
;           else { x3 = XRF[(16 * rg + 0) * 128 + ch]; x2 = XRF[(16 * rg + 1) * 128 + ch]; x1 = XRF[(16 * rg + 2) * 128 + ch]; }
; #pragma unroll
;           for (int i = 0; i < 16; ++i) { const float x0 = XRF[(16 * rg + 3 + i) * 128 + ch]; xc[i] = __builtin_fmaf(w3, x0, __builtin_fmaf(w2, x1, __builtin_fmaf(w1, x2, __builtin_fmaf(w0, x3, bc)))); x3 = x2; x2 = x1; x1 = x0;
;               XCB[(16 * rg + i) * 136 + ch] = (bf16)pg8::cvt_pk_bf16(xc[i], xc[i]); } }
;         __syncthreads();
; #pragma unroll
;         for (int mt = 0; mt < 4; ++mt) { f32x4 d0 = (f32x4){0.f, 0.f, 0.f, 0.f}, d1 = d0;
; #pragma unroll
;             for (int kk = 0; kk < 4; ++kk) { const bf16x8 a = *(const LAS bf16x8*)(XCB + (16 * mt + jj) * 136 + 32 * kk + 8 * q);
;                 d0 = __builtin_amdgcn_mfma_f32_16x16x32_bf16(a, Bf[0][kk], d0, 0, 0, 0); d1 = __builtin_amdgcn_mfma_f32_16x16x32_bf16(a, Bf[1][kk], d1, 0, 0, 0); }
; #pragma unroll
;             for (int ep = 0; ep < 2; ++ep) { const int row = 16 * mt + 4 * q + 2 * ep;
;                 const f32x2 t0 = (f32x2){d0[2 * ep], d0[2 * ep + 1]} * (f32x2){-1.4426950408889634f, -1.4426950408889634f} + (f32x2){nb0, nb0};
;                 const f32x2 t1 = (f32x2){d1[2 * ep], d1[2 * ep + 1]} * (f32x2){-1.4426950408889634f, -1.4426950408889634f} + (f32x2){nb1, nb1};
;                 const f32x2 e0 = (f32x2){__builtin_amdgcn_exp2f(t0.x), __builtin_amdgcn_exp2f(t0.y)} + (f32x2){1.f, 1.f}, e1 = (f32x2){__builtin_amdgcn_exp2f(t1.x), __builtin_amdgcn_exp2f(t1.y)} + (f32x2){1.f, 1.f};
;                 GT[(gate * 64 + row) * GTP + cb + jj] = __builtin_amdgcn_rcpf(e0.x); GT[(gate * 64 + row + 1) * GTP + cb + jj] = __builtin_amdgcn_rcpf(e0.y);
;                 GT[(gate * 64 + row) * GTP + cb + 16 + jj] = __builtin_amdgcn_rcpf(e1.x); GT[(gate * 64 + row + 1) * GTP + cb + 16 + jj] = __builtin_amdgcn_rcpf(e1.y); } }
.LBB0_2328:
	ds_read_b32 v172, v162 offset:1536
	ds_read_b32 v173, v162 offset:2048
	ds_read_b32 v174, v162 offset:2560
	ds_read_b32 v175, v162 offset:3072
	ds_read_b32 v176, v162 offset:3584
	ds_read_b32 v177, v162 offset:4096
	ds_read_b32 v178, v162 offset:4608
	ds_read_b32 v179, v162 offset:5120
	ds_read_b32 v180, v162 offset:5632
	ds_read_b32 v181, v162 offset:6144
	ds_read_b32 v182, v162 offset:6656
	ds_read_b32 v183, v162 offset:7168
	ds_read_b32 v184, v162 offset:7680
	ds_read_b32 v185, v162 offset:8192
	ds_read_b32 v186, v162 offset:8704
	ds_read_b32 v187, v162 offset:9216
	s_waitcnt lgkmcnt(0)
	v_fma_f32 v78, v168, v70, v164
	v_fmac_f32_e32 v78, v167, v71
	v_fmac_f32_e32 v78, v166, v11
	v_fma_f32 v79, v168, v71, v164
	v_fmac_f32_e32 v78, v165, v172
	v_cvt_pk_bf16_f32 v57, v78, v78
	v_fmac_f32_e32 v79, v167, v11
	v_fmac_f32_e32 v79, v166, v172
	ds_write_b16 v151, v57 offset:50688
	v_fma_f32 v86, v168, v11, v164
	v_fmac_f32_e32 v79, v165, v173
	v_cvt_pk_bf16_f32 v57, v79, v79
	v_fmac_f32_e32 v86, v167, v172
	v_fmac_f32_e32 v86, v166, v173
	ds_write_b16 v151, v57 offset:50960
	v_fma_f32 v87, v168, v172, v164
	v_fmac_f32_e32 v86, v165, v174
	v_cvt_pk_bf16_f32 v11, v86, v86
	v_fmac_f32_e32 v87, v167, v173
	v_fmac_f32_e32 v87, v166, v174
	ds_write_b16 v152, v11 offset:50688
	v_fma_f32 v84, v168, v173, v164
	v_fmac_f32_e32 v87, v165, v175
	v_cvt_pk_bf16_f32 v1, v87, v87
	v_fmac_f32_e32 v84, v167, v174
	v_fmac_f32_e32 v84, v166, v175
	ds_write_b16 v151, v1 offset:51504
	v_fma_f32 v85, v168, v174, v164
	v_fmac_f32_e32 v84, v165, v176
	v_cvt_pk_bf16_f32 v1, v84, v84
	v_fmac_f32_e32 v85, v167, v175
	v_fmac_f32_e32 v85, v166, v176
	ds_write_b16 v152, v1 offset:51232
	v_fma_f32 v82, v168, v175, v164
	v_fmac_f32_e32 v85, v165, v177
	v_cvt_pk_bf16_f32 v1, v85, v85
	v_fmac_f32_e32 v82, v167, v176
	v_fmac_f32_e32 v82, v166, v177
	ds_write_b16 v151, v1 offset:52048
	v_fma_f32 v83, v168, v176, v164
	v_fmac_f32_e32 v82, v165, v178
	v_cvt_pk_bf16_f32 v1, v82, v82
	v_fmac_f32_e32 v83, v167, v177
	v_fmac_f32_e32 v83, v166, v178
	ds_write_b16 v152, v1 offset:51776
	v_fma_f32 v80, v168, v177, v164
	v_fmac_f32_e32 v83, v165, v179
	v_cvt_pk_bf16_f32 v1, v83, v83
	v_fmac_f32_e32 v80, v167, v178
	v_fmac_f32_e32 v80, v166, v179
	ds_write_b16 v151, v1 offset:52592
	v_fma_f32 v81, v168, v178, v164
	v_fmac_f32_e32 v80, v165, v180
	v_cvt_pk_bf16_f32 v1, v80, v80
	v_fmac_f32_e32 v81, v167, v179
	v_fmac_f32_e32 v81, v166, v180
	ds_write_b16 v152, v1 offset:52320
	v_fma_f32 v76, v168, v179, v164
	v_fmac_f32_e32 v81, v165, v181
	v_cvt_pk_bf16_f32 v1, v81, v81
	v_fmac_f32_e32 v76, v167, v180
	v_fmac_f32_e32 v76, v166, v181
	ds_write_b16 v151, v1 offset:53136
	v_fma_f32 v77, v168, v180, v164
	v_fmac_f32_e32 v76, v165, v182
	v_cvt_pk_bf16_f32 v1, v76, v76
	v_fmac_f32_e32 v77, v167, v181
	v_fmac_f32_e32 v77, v166, v182
	ds_write_b16 v152, v1 offset:52864
	v_fma_f32 v74, v168, v181, v164
	v_fmac_f32_e32 v77, v165, v183
	v_cvt_pk_bf16_f32 v1, v77, v77
	v_fmac_f32_e32 v74, v167, v182
	v_fmac_f32_e32 v74, v166, v183
	ds_write_b16 v151, v1 offset:53680
	v_fma_f32 v75, v168, v182, v164
	v_fmac_f32_e32 v74, v165, v184
	v_cvt_pk_bf16_f32 v1, v74, v74
	v_fmac_f32_e32 v75, v167, v183
	v_fmac_f32_e32 v75, v166, v184
	ds_write_b16 v152, v1 offset:53408
	v_fma_f32 v72, v168, v183, v164
	v_fmac_f32_e32 v75, v165, v185
	v_cvt_pk_bf16_f32 v1, v75, v75
	v_fmac_f32_e32 v72, v167, v184
	v_fmac_f32_e32 v72, v166, v185
	ds_write_b16 v151, v1 offset:54224
	v_fma_f32 v73, v168, v184, v164
	v_fmac_f32_e32 v72, v165, v186
	v_cvt_pk_bf16_f32 v1, v72, v72
	v_fmac_f32_e32 v73, v167, v185
	v_fmac_f32_e32 v73, v166, v186
	ds_write_b16 v152, v1 offset:53952
	s_and_b64 vcc, exec, s[40:41]
	v_fmac_f32_e32 v73, v165, v187
	v_cvt_pk_bf16_f32 v1, v73, v73
	ds_write_b16 v151, v1 offset:54768
	s_waitcnt lgkmcnt(0)
	s_barrier
	ds_read_b128 v[88:91], v153 offset:50688
	ds_read_b128 v[92:95], v153 offset:50752
	s_waitcnt lgkmcnt(1)
	v_mfma_f32_16x16x32_bf16 v[96:99], v[88:91], v[24:27], 0
	s_mov_b64 s[44:45], -1
	v_mfma_f32_16x16x32_bf16 v[88:91], v[88:91], v[40:43], 0
	s_waitcnt lgkmcnt(0)
	v_mfma_f32_16x16x32_bf16 v[96:99], v[92:95], v[28:31], v[96:99]
	v_mfma_f32_16x16x32_bf16 v[88:91], v[92:95], v[44:47], v[88:91]
	ds_read_b128 v[92:95], v153 offset:50816
	ds_read_b128 v[100:103], v153 offset:50880
	s_waitcnt lgkmcnt(1)
	v_mfma_f32_16x16x32_bf16 v[96:99], v[92:95], v[32:35], v[96:99]
	v_mfma_f32_16x16x32_bf16 v[88:91], v[92:95], v[48:51], v[88:91]
	s_waitcnt lgkmcnt(0)
	v_mfma_f32_16x16x32_bf16 v[92:95], v[100:103], v[36:39], v[96:99]
	v_mfma_f32_16x16x32_bf16 v[88:91], v[100:103], v[52:55], v[88:91]
	s_nop 6
	v_fma_f32 v70, -v92, s84, v66
	v_fma_f32 v71, -v93, s84, v66
	v_pk_fma_f32 v[88:89], v[88:89], s[84:85], v[68:69] op_sel:[0,0,1] op_sel_hi:[1,0,1] neg_lo:[1,0,0] neg_hi:[1,0,0]
	v_exp_f32_e32 v70, v70
	v_exp_f32_e32 v71, v71
	v_exp_f32_e32 v88, v88
	v_exp_f32_e32 v89, v89
	v_pk_fma_f32 v[90:91], v[90:91], s[84:85], v[68:69] op_sel:[0,0,1] op_sel_hi:[1,0,1] neg_lo:[1,0,0] neg_hi:[1,0,0]
	v_pk_add_f32 v[70:71], v[70:71], 1.0 op_sel_hi:[1,0]
	v_exp_f32_e32 v90, v90
	v_pk_add_f32 v[88:89], v[88:89], 1.0 op_sel_hi:[1,0]
	v_rcp_f32_e32 v1, v70
	v_rcp_f32_e32 v11, v71
	v_pk_fma_f32 v[70:71], v[94:95], s[84:85], v[66:67] op_sel_hi:[1,0,0] neg_lo:[1,0,0] neg_hi:[1,0,0]
	v_rcp_f32_e32 v57, v88
	v_exp_f32_e32 v70, v70
	v_exp_f32_e32 v71, v71
	v_exp_f32_e32 v91, v91
	ds_write2_b32 v133, v1, v57 offset1:16
	v_rcp_f32_e32 v1, v89
	v_pk_add_f32 v[70:71], v[70:71], 1.0 op_sel_hi:[1,0]
	v_pk_add_f32 v[88:89], v[90:91], 1.0 op_sel_hi:[1,0]
	v_rcp_f32_e32 v57, v70
	v_rcp_f32_e32 v70, v88
	v_rcp_f32_e32 v65, v71
	v_rcp_f32_e32 v71, v89
	ds_write2_b32 v133, v11, v1 offset0:132 offset1:148
	v_add_u32_e32 v1, 0x400, v133
	ds_write2_b32 v1, v57, v70 offset0:8 offset1:24
	ds_write2_b32 v134, v65, v71 offset0:132 offset1:148
	ds_read_b128 v[88:91], v153 offset:55040
	ds_read_b128 v[92:95], v153 offset:55104
	s_waitcnt lgkmcnt(1)
; #define LAS __attribute__((address_space(3)))
; template <int MODE>
; __device__ __forceinline__ void rnn_phase(const RnnP& P, LAS unsigned char* lds, int G, int bid, int nunits) {
;     ...
; #pragma unroll
;         for (int mt = 0; mt < 4; ++mt) { f32x4 d0 = (f32x4){0.f, 0.f, 0.f, 0.f}, d1 = d0;
; #pragma unroll
;             for (int kk = 0; kk < 4; ++kk) { const bf16x8 a = *(const LAS bf16x8*)(XCB + (16 * mt + jj) * 136 + 32 * kk + 8 * q);
;                 d0 = __builtin_amdgcn_mfma_f32_16x16x32_bf16(a, Bf[0][kk], d0, 0, 0, 0); d1 = __builtin_amdgcn_mfma_f32_16x16x32_bf16(a, Bf[1][kk], d1, 0, 0, 0); }
; #pragma unroll
;             for (int ep = 0; ep < 2; ++ep) { const int row = 16 * mt + 4 * q + 2 * ep;
;                 const f32x2 t0 = (f32x2){d0[2 * ep], d0[2 * ep + 1]} * (f32x2){-1.4426950408889634f, -1.4426950408889634f} + (f32x2){nb0, nb0};
;                 const f32x2 t1 = (f32x2){d1[2 * ep], d1[2 * ep + 1]} * (f32x2){-1.4426950408889634f, -1.4426950408889634f} + (f32x2){nb1, nb1};
;                 const f32x2 e0 = (f32x2){__builtin_amdgcn_exp2f(t0.x), __builtin_amdgcn_exp2f(t0.y)} + (f32x2){1.f, 1.f}, e1 = (f32x2){__builtin_amdgcn_exp2f(t1.x), __builtin_amdgcn_exp2f(t1.y)} + (f32x2){1.f, 1.f};
;                 GT[(gate * 64 + row) * GTP + cb + jj] = __builtin_amdgcn_rcpf(e0.x); GT[(gate * 64 + row + 1) * GTP + cb + jj] = __builtin_amdgcn_rcpf(e0.y);
;                 GT[(gate * 64 + row) * GTP + cb + 16 + jj] = __builtin_amdgcn_rcpf(e1.x); GT[(gate * 64 + row + 1) * GTP + cb + 16 + jj] = __builtin_amdgcn_rcpf(e1.y); } }
;         __syncthreads();
	v_mfma_f32_16x16x32_bf16 v[96:99], v[88:91], v[24:27], 0
	v_add_u32_e32 v65, 0x2000, v133
	v_mfma_f32_16x16x32_bf16 v[88:91], v[88:91], v[40:43], 0
	s_waitcnt lgkmcnt(0)
	v_mfma_f32_16x16x32_bf16 v[96:99], v[92:95], v[28:31], v[96:99]
	v_mfma_f32_16x16x32_bf16 v[88:91], v[92:95], v[44:47], v[88:91]
	ds_read_b128 v[92:95], v153 offset:55168
	ds_read_b128 v[100:103], v153 offset:55232
	s_waitcnt lgkmcnt(1)
	v_mfma_f32_16x16x32_bf16 v[96:99], v[92:95], v[32:35], v[96:99]
	v_mfma_f32_16x16x32_bf16 v[88:91], v[92:95], v[48:51], v[88:91]
	s_waitcnt lgkmcnt(0)
	v_mfma_f32_16x16x32_bf16 v[92:95], v[100:103], v[36:39], v[96:99]
	v_mfma_f32_16x16x32_bf16 v[88:91], v[100:103], v[52:55], v[88:91]
	s_nop 6
	v_fma_f32 v70, -v92, s84, v66
	v_fma_f32 v71, -v93, s84, v66
	v_pk_fma_f32 v[88:89], v[88:89], s[84:85], v[68:69] op_sel:[0,0,1] op_sel_hi:[1,0,1] neg_lo:[1,0,0] neg_hi:[1,0,0]
	v_exp_f32_e32 v70, v70
	v_exp_f32_e32 v71, v71
	v_exp_f32_e32 v88, v88
	v_exp_f32_e32 v89, v89
	v_pk_fma_f32 v[90:91], v[90:91], s[84:85], v[68:69] op_sel:[0,0,1] op_sel_hi:[1,0,1] neg_lo:[1,0,0] neg_hi:[1,0,0]
	v_pk_add_f32 v[70:71], v[70:71], 1.0 op_sel_hi:[1,0]
	v_exp_f32_e32 v90, v90
	v_pk_add_f32 v[88:89], v[88:89], 1.0 op_sel_hi:[1,0]
	v_rcp_f32_e32 v1, v70
	v_rcp_f32_e32 v11, v71
	v_pk_fma_f32 v[70:71], v[94:95], s[84:85], v[66:67] op_sel_hi:[1,0,0] neg_lo:[1,0,0] neg_hi:[1,0,0]
	v_rcp_f32_e32 v57, v88
	v_exp_f32_e32 v70, v70
	v_exp_f32_e32 v71, v71
	v_exp_f32_e32 v91, v91
	ds_write2_b32 v65, v1, v57 offset0:64 offset1:80
	v_rcp_f32_e32 v1, v89
	v_pk_add_f32 v[70:71], v[70:71], 1.0 op_sel_hi:[1,0]
	v_pk_add_f32 v[88:89], v[90:91], 1.0 op_sel_hi:[1,0]
	v_rcp_f32_e32 v57, v70
	v_rcp_f32_e32 v70, v88
	v_rcp_f32_e32 v65, v71
	v_rcp_f32_e32 v71, v89
	ds_write2_b32 v135, v11, v1 offset0:132 offset1:148
	v_add_u32_e32 v1, 0x2400, v133
	ds_write2_b32 v1, v57, v70 offset0:72 offset1:88
	ds_write2_b32 v136, v65, v71 offset0:132 offset1:148
	ds_read_b128 v[88:91], v153 offset:59392
	ds_read_b128 v[92:95], v153 offset:59456
	s_waitcnt lgkmcnt(1)
	v_mfma_f32_16x16x32_bf16 v[96:99], v[88:91], v[24:27], 0
	v_add_u32_e32 v65, 0x4000, v133
	v_mfma_f32_16x16x32_bf16 v[88:91], v[88:91], v[40:43], 0
	s_waitcnt lgkmcnt(0)
	v_mfma_f32_16x16x32_bf16 v[96:99], v[92:95], v[28:31], v[96:99]
	v_mfma_f32_16x16x32_bf16 v[88:91], v[92:95], v[44:47], v[88:91]
	ds_read_b128 v[92:95], v153 offset:59520
	ds_read_b128 v[100:103], v153 offset:59584
	s_waitcnt lgkmcnt(1)
	v_mfma_f32_16x16x32_bf16 v[96:99], v[92:95], v[32:35], v[96:99]
	v_mfma_f32_16x16x32_bf16 v[88:91], v[92:95], v[48:51], v[88:91]
	s_waitcnt lgkmcnt(0)
	v_mfma_f32_16x16x32_bf16 v[92:95], v[100:103], v[36:39], v[96:99]
	v_mfma_f32_16x16x32_bf16 v[88:91], v[100:103], v[52:55], v[88:91]
	s_nop 6
	v_fma_f32 v70, -v92, s84, v66
	v_fma_f32 v71, -v93, s84, v66
	v_pk_fma_f32 v[88:89], v[88:89], s[84:85], v[68:69] op_sel:[0,0,1] op_sel_hi:[1,0,1] neg_lo:[1,0,0] neg_hi:[1,0,0]
	v_exp_f32_e32 v70, v70
	v_exp_f32_e32 v71, v71
	v_exp_f32_e32 v88, v88
	v_exp_f32_e32 v89, v89
	v_pk_fma_f32 v[90:91], v[90:91], s[84:85], v[68:69] op_sel:[0,0,1] op_sel_hi:[1,0,1] neg_lo:[1,0,0] neg_hi:[1,0,0]
	v_pk_add_f32 v[70:71], v[70:71], 1.0 op_sel_hi:[1,0]
	v_exp_f32_e32 v90, v90
	v_pk_add_f32 v[88:89], v[88:89], 1.0 op_sel_hi:[1,0]
	v_rcp_f32_e32 v1, v70
	v_rcp_f32_e32 v11, v71
	v_pk_fma_f32 v[70:71], v[94:95], s[84:85], v[66:67] op_sel_hi:[1,0,0] neg_lo:[1,0,0] neg_hi:[1,0,0]
	v_rcp_f32_e32 v57, v88
	v_exp_f32_e32 v70, v70
	v_exp_f32_e32 v71, v71
	v_exp_f32_e32 v91, v91
	ds_write2_b32 v65, v1, v57 offset0:128 offset1:144
	v_rcp_f32_e32 v1, v89
	v_pk_add_f32 v[70:71], v[70:71], 1.0 op_sel_hi:[1,0]
	v_pk_add_f32 v[88:89], v[90:91], 1.0 op_sel_hi:[1,0]
	v_rcp_f32_e32 v57, v70
	v_rcp_f32_e32 v70, v88
	v_rcp_f32_e32 v65, v71
	v_rcp_f32_e32 v71, v89
	ds_write2_b32 v137, v11, v1 offset0:132 offset1:148
	v_add_u32_e32 v1, 0x4400, v133
	ds_write2_b32 v1, v57, v70 offset0:136 offset1:152
	ds_write2_b32 v138, v65, v71 offset0:132 offset1:148
	ds_read_b128 v[88:91], v153 offset:63744
	ds_read_b128 v[92:95], v153 offset:63808
	s_waitcnt lgkmcnt(1)
	v_mfma_f32_16x16x32_bf16 v[96:99], v[88:91], v[24:27], 0
	v_add_u32_e32 v65, 0x6000, v133
	v_mfma_f32_16x16x32_bf16 v[88:91], v[88:91], v[40:43], 0
	s_waitcnt lgkmcnt(0)
	v_mfma_f32_16x16x32_bf16 v[96:99], v[92:95], v[28:31], v[96:99]
	v_mfma_f32_16x16x32_bf16 v[88:91], v[92:95], v[44:47], v[88:91]
	ds_read_b128 v[92:95], v153 offset:63872
	ds_read_b128 v[100:103], v153 offset:63936
	s_waitcnt lgkmcnt(1)
	v_mfma_f32_16x16x32_bf16 v[96:99], v[92:95], v[32:35], v[96:99]
	v_mfma_f32_16x16x32_bf16 v[88:91], v[92:95], v[48:51], v[88:91]
	s_waitcnt lgkmcnt(0)
	v_mfma_f32_16x16x32_bf16 v[92:95], v[100:103], v[36:39], v[96:99]
	v_mfma_f32_16x16x32_bf16 v[88:91], v[100:103], v[52:55], v[88:91]
	s_nop 6
	v_fma_f32 v70, -v92, s84, v66
	v_fma_f32 v71, -v93, s84, v66
	v_pk_fma_f32 v[88:89], v[88:89], s[84:85], v[68:69] op_sel:[0,0,1] op_sel_hi:[1,0,1] neg_lo:[1,0,0] neg_hi:[1,0,0]
	v_exp_f32_e32 v70, v70
	v_exp_f32_e32 v71, v71
	v_exp_f32_e32 v88, v88
	v_exp_f32_e32 v89, v89
	v_pk_fma_f32 v[90:91], v[90:91], s[84:85], v[68:69] op_sel:[0,0,1] op_sel_hi:[1,0,1] neg_lo:[1,0,0] neg_hi:[1,0,0]
	v_pk_add_f32 v[70:71], v[70:71], 1.0 op_sel_hi:[1,0]
	v_exp_f32_e32 v90, v90
	v_pk_add_f32 v[88:89], v[88:89], 1.0 op_sel_hi:[1,0]
	v_rcp_f32_e32 v1, v70
	v_rcp_f32_e32 v11, v71
	v_pk_fma_f32 v[70:71], v[94:95], s[84:85], v[66:67] op_sel_hi:[1,0,0] neg_lo:[1,0,0] neg_hi:[1,0,0]
	v_rcp_f32_e32 v57, v88
	v_exp_f32_e32 v70, v70
	v_exp_f32_e32 v71, v71
	v_exp_f32_e32 v91, v91
	ds_write2_b32 v65, v1, v57 offset0:192 offset1:208
	v_rcp_f32_e32 v1, v89
	v_pk_add_f32 v[70:71], v[70:71], 1.0 op_sel_hi:[1,0]
	v_pk_add_f32 v[88:89], v[90:91], 1.0 op_sel_hi:[1,0]
	v_rcp_f32_e32 v57, v70
	v_rcp_f32_e32 v70, v88
	v_rcp_f32_e32 v65, v71
	v_rcp_f32_e32 v71, v89
	ds_write2_b32 v139, v11, v1 offset0:132 offset1:148
	v_add_u32_e32 v1, 0x6400, v133
	ds_write2_b32 v1, v57, v70 offset0:200 offset1:216
	ds_write2_b32 v140, v65, v71 offset0:132 offset1:148
	v_add_u32_e32 v1, 0x8400, v141
	s_waitcnt lgkmcnt(0)
	s_barrier
; template <int MODE>
; __device__ __forceinline__ void rnn_phase(const RnnP& P, LAS unsigned char* lds, int G, int bid, int nunits) {
;     ...
;         float Lr[16], Pr[16];
;         { float L = 0.f, Pp = 1.f;
; #pragma unroll
;           for (int ip = 0; ip < 8; ++ip) { const int i = 2 * ip;
;               const f32x2 r2 = (f32x2){GT[(16 * rg + i) * GTP + ch], GT[(16 * rg + i + 1) * GTP + ch]}, ig2 = (f32x2){GT[(64 + 16 * rg + i) * GTP + ch], GT[(64 + 16 * rg + i + 1) * GTP + ch]};
;     ...
;             float Hin;
;             if (samp) { Hin = P.st_h[(size_t)((R0 >> 4) + rg) * 2048 + chg]; }
	ds_read2_b32 v[88:89], v141 offset1:132
	ds_read2_b32 v[102:103], v1 offset1:132
	ds_read2_b32 v[118:119], v142 offset1:132
	v_add_u32_e32 v1, 0x8800, v141
	ds_read2_b32 v[94:95], v1 offset0:8 offset1:140
	ds_read2_b32 v[100:101], v143 offset1:132
	v_add_u32_e32 v1, 0x8c00, v141
	ds_read2_b32 v[98:99], v1 offset0:16 offset1:148
	ds_read2_b32 v[96:97], v144 offset1:132
	v_add_u32_e32 v1, 0x9000, v141
	ds_read2_b32 v[116:117], v1 offset0:24 offset1:156
	ds_read2_b32 v[92:93], v145 offset1:132
	v_add_u32_e32 v1, 0x9400, v141
	ds_read2_b32 v[114:115], v1 offset0:32 offset1:164
	ds_read2_b32 v[90:91], v146 offset1:132
	v_add_u32_e32 v1, 0x9800, v141
	ds_read2_b32 v[112:113], v1 offset0:40 offset1:172
	ds_read2_b32 v[110:111], v147 offset1:132
	v_add_u32_e32 v1, 0x9c00, v141
	ds_read2_b32 v[108:109], v1 offset0:48 offset1:180
	ds_read2_b32 v[106:107], v148 offset1:132
	v_add_u32_e32 v1, 0xa000, v141
	ds_read2_b32 v[104:105], v1 offset0:56 offset1:188
	s_cbranch_vccnz .LBB0_2330
	s_ashr_i32 s44, s0, 4
	v_add_u32_e32 v70, s44, v124
	v_ashrrev_i32_e32 v71, 31, v70
	v_lshlrev_b64 v[70:71], 13, v[70:71]
	v_mov_b32_e32 v65, v10
	v_lshl_add_u64 v[70:71], s[48:49], 0, v[70:71]
	v_lshl_add_u64 v[70:71], v[64:65], 2, v[70:71]
	global_load_dword v70, v[70:71], off
	s_mov_b64 s[44:45], 0

; __device__ __forceinline__ unsigned cvt_pk_bf16(float lo, float hi) { unsigned r; asm volatile("v_cvt_pk_bf16_f32 %0, %1, %2" : "=v"(r) : "v"(lo), "v"(hi)); return r; }
; template <int MODE>
; __device__ __forceinline__ void rnn_phase(const RnnP& P, LAS unsigned char* lds, int G, int bid, int nunits) {
;     ...
;             float qs[16];
; #pragma unroll
;             for (int ip = 0; ip < 8; ++ip) { const int i = 2 * ip;
;                 const f32x2 h2 = (f32x2){Pr[i], Pr[i + 1]} * (f32x2){Hin, Hin} + (f32x2){Lr[i], Lr[i + 1]};
;                 const f32x2 y2 = (f32x2){bf2f(YGS[(16 * rg + i) * 128 + ch]), bf2f(YGS[(16 * rg + i + 1) * 128 + ch])};
;                 const f32x2 u2 = y2 * ((y2 * y2) * (f32x2){-0.10294322f, -0.10294322f} + (f32x2){-2.3022077f, -2.3022077f});
;                 const f32x2 e2 = (f32x2){__builtin_amdgcn_exp2f(u2.x), __builtin_amdgcn_exp2f(u2.y)} + (f32x2){1.f, 1.f};
;                 const f32x2 o2 = h2 * (y2 * (f32x2){__builtin_amdgcn_rcpf(e2.x), __builtin_amdgcn_rcpf(e2.y)});
;                 const unsigned pk = pg8::cvt_pk_bf16(o2.x, o2.y);
;                 YGS[(16 * rg + i) * 128 + ch] = (bf16)(pk & 0xffffu); YGS[(16 * rg + i + 1) * 128 + ch] = (bf16)(pk >> 16);
;                 const f32x2 q2 = o2 * o2; qs[i] = q2.x; qs[i + 1] = q2.y;
.LBB0_2338:
	ds_read_u16 v189, v154 offset:34304
	ds_read_u16 v190, v154 offset:34560
	ds_read_u16 v191, v154 offset:34816
	ds_read_u16 v192, v154 offset:35072
	ds_read_u16 v193, v154 offset:35328
	ds_read_u16 v194, v154 offset:35584
	ds_read_u16 v195, v154 offset:35840
	ds_read_u16 v196, v154 offset:36096
	ds_read_u16 v197, v154 offset:36352
	ds_read_u16 v198, v154 offset:36608
	ds_read_u16 v199, v154 offset:36864
	ds_read_u16 v200, v154 offset:37120
	ds_read_u16 v201, v154 offset:37376
	ds_read_u16 v202, v154 offset:37632
	ds_read_u16 v203, v154 offset:37888
	ds_read_u16 v204, v154 offset:38144
	s_mov_b32 s42, 0xc013575f
	v_mov_b64_e32 v[104:105], s[42:43]
	s_waitcnt vmcnt(0)
	v_pk_fma_f32 v[88:89], v[88:89], v[70:71], v[102:103] op_sel_hi:[1, 0, 1]
	s_waitcnt lgkmcnt(0)
	v_lshlrev_b32_e32 v106, 16, v189
	v_lshlrev_b32_e32 v107, 16, v190
	v_pk_mul_f32 v[108:109], v[106:107], v[106:107]
	v_pk_fma_f32 v[94:95], v[100:101], v[70:71], v[94:95] op_sel_hi:[1, 0, 1]
	v_pk_fma_f32 v[108:109], v[108:109], s[86:87], v[104:105] op_sel_hi:[1, 0, 0] neg_lo:[1, 0, 0] neg_hi:[1, 0, 0]
	v_pk_fma_f32 v[96:97], v[98:99], v[70:71], v[96:97] op_sel_hi:[1, 0, 1]
	v_pk_mul_f32 v[108:109], v[108:109], v[106:107]
	v_pk_fma_f32 v[84:85], v[92:93], v[70:71], v[84:85] op_sel_hi:[1, 0, 1]
	v_exp_f32_e32 v108, v108
	v_exp_f32_e32 v109, v109
	v_pk_fma_f32 v[86:87], v[90:91], v[70:71], v[86:87] op_sel_hi:[1, 0, 1]
	v_pk_fma_f32 v[76:77], v[82:83], v[70:71], v[76:77] op_sel_hi:[1, 0, 1]
	v_pk_fma_f32 v[78:79], v[80:81], v[70:71], v[78:79] op_sel_hi:[1, 0, 1]
	v_pk_add_f32 v[108:109], v[108:109], 1.0 op_sel_hi:[1, 0]
	v_pk_fma_f32 v[72:73], v[74:75], v[70:71], v[72:73] op_sel_hi:[1, 0, 1]
	v_rcp_f32_e32 v108, v108
	v_rcp_f32_e32 v109, v109
	s_and_b64 vcc, exec, s[40:41]
	v_pk_mul_f32 v[102:103], v[108:109], v[106:107]
	s_nop 0
	v_pk_mul_f32 v[88:89], v[88:89], v[102:103]
	s_nop 0
	v_cvt_pk_bf16_f32 v1, v88, v89
	ds_write_b16 v154, v1 offset:34304
	ds_write_b16_d16_hi v154, v1 offset:34560
	v_lshlrev_b32_e32 v102, 16, v191
	v_lshlrev_b32_e32 v103, 16, v192
	v_pk_mul_f32 v[106:107], v[102:103], v[102:103]
	s_nop 0
	v_pk_fma_f32 v[106:107], v[106:107], s[86:87], v[104:105] op_sel_hi:[1, 0, 0] neg_lo:[1, 0, 0] neg_hi:[1, 0, 0]
	s_nop 0
	v_pk_mul_f32 v[106:107], v[106:107], v[102:103]
	s_nop 0
	v_exp_f32_e32 v106, v106
	v_exp_f32_e32 v107, v107
	s_nop 0
	v_pk_add_f32 v[106:107], v[106:107], 1.0 op_sel_hi:[1, 0]
	s_nop 0
	v_rcp_f32_e32 v106, v106
	v_rcp_f32_e32 v107, v107
	s_nop 0
	v_pk_mul_f32 v[100:101], v[106:107], v[102:103]
	s_nop 0
	v_pk_mul_f32 v[94:95], v[94:95], v[100:101]
	s_nop 0
	v_cvt_pk_bf16_f32 v1, v94, v95
	ds_write_b16 v154, v1 offset:34816
	ds_write_b16_d16_hi v154, v1 offset:35072
	v_lshlrev_b32_e32 v100, 16, v193
	v_lshlrev_b32_e32 v101, 16, v194
	v_pk_mul_f32 v[102:103], v[100:101], v[100:101]
	s_nop 0
	v_pk_fma_f32 v[102:103], v[102:103], s[86:87], v[104:105] op_sel_hi:[1, 0, 0] neg_lo:[1, 0, 0] neg_hi:[1, 0, 0]
	s_nop 0
	v_pk_mul_f32 v[102:103], v[102:103], v[100:101]
	s_nop 0
	v_exp_f32_e32 v102, v102
	v_exp_f32_e32 v103, v103
	s_nop 0
	v_pk_add_f32 v[102:103], v[102:103], 1.0 op_sel_hi:[1, 0]
	s_nop 0
	v_rcp_f32_e32 v102, v102
	v_rcp_f32_e32 v103, v103
	s_nop 0
	v_pk_mul_f32 v[98:99], v[102:103], v[100:101]
	s_nop 0
	v_pk_mul_f32 v[96:97], v[96:97], v[98:99]
	s_nop 0
	v_cvt_pk_bf16_f32 v1, v96, v97
	ds_write_b16 v154, v1 offset:35328
	ds_write_b16_d16_hi v154, v1 offset:35584
	v_lshlrev_b32_e32 v98, 16, v195
	v_lshlrev_b32_e32 v99, 16, v196
	v_pk_mul_f32 v[100:101], v[98:99], v[98:99]
	s_nop 0
	v_pk_fma_f32 v[100:101], v[100:101], s[86:87], v[104:105] op_sel_hi:[1, 0, 0] neg_lo:[1, 0, 0] neg_hi:[1, 0, 0]
	s_nop 0
	v_pk_mul_f32 v[100:101], v[100:101], v[98:99]
	s_nop 0
	v_exp_f32_e32 v100, v100
	v_exp_f32_e32 v101, v101
	s_nop 0
	v_pk_add_f32 v[100:101], v[100:101], 1.0 op_sel_hi:[1, 0]
	s_nop 0
	v_rcp_f32_e32 v100, v100
	v_rcp_f32_e32 v101, v101
	s_nop 0
	v_pk_mul_f32 v[92:93], v[100:101], v[98:99]
	s_nop 0
	v_pk_mul_f32 v[84:85], v[84:85], v[92:93]
	s_nop 0
	v_cvt_pk_bf16_f32 v1, v84, v85
	ds_write_b16 v154, v1 offset:35840
	ds_write_b16_d16_hi v154, v1 offset:36096
	v_lshlrev_b32_e32 v92, 16, v197
	v_lshlrev_b32_e32 v93, 16, v198
	v_pk_mul_f32 v[98:99], v[92:93], v[92:93]
	s_nop 0
	v_pk_fma_f32 v[98:99], v[98:99], s[86:87], v[104:105] op_sel_hi:[1, 0, 0] neg_lo:[1, 0, 0] neg_hi:[1, 0, 0]
	s_nop 0
	v_pk_mul_f32 v[98:99], v[98:99], v[92:93]
	s_nop 0
	v_exp_f32_e32 v98, v98
	v_exp_f32_e32 v99, v99
	s_nop 0
	v_pk_add_f32 v[98:99], v[98:99], 1.0 op_sel_hi:[1, 0]
	s_nop 0
	v_rcp_f32_e32 v98, v98
	v_rcp_f32_e32 v99, v99
	s_nop 0
	v_pk_mul_f32 v[90:91], v[98:99], v[92:93]
	s_nop 0
	v_pk_mul_f32 v[86:87], v[86:87], v[90:91]
	s_nop 0
	v_cvt_pk_bf16_f32 v1, v86, v87
	ds_write_b16 v154, v1 offset:36352
	ds_write_b16_d16_hi v154, v1 offset:36608
	v_lshlrev_b32_e32 v90, 16, v199
	v_lshlrev_b32_e32 v91, 16, v200
	v_pk_mul_f32 v[92:93], v[90:91], v[90:91]
	s_nop 0
	v_pk_fma_f32 v[92:93], v[92:93], s[86:87], v[104:105] op_sel_hi:[1, 0, 0] neg_lo:[1, 0, 0] neg_hi:[1, 0, 0]
	s_nop 0
	v_pk_mul_f32 v[92:93], v[92:93], v[90:91]
	s_nop 0
	v_exp_f32_e32 v92, v92
	v_exp_f32_e32 v93, v93
	s_nop 0
	v_pk_add_f32 v[92:93], v[92:93], 1.0 op_sel_hi:[1, 0]
	s_nop 0
	v_rcp_f32_e32 v92, v92
	v_rcp_f32_e32 v93, v93
	s_nop 0
	v_pk_mul_f32 v[82:83], v[92:93], v[90:91]
	s_nop 0
	v_pk_mul_f32 v[76:77], v[76:77], v[82:83]
	s_nop 0
	v_cvt_pk_bf16_f32 v1, v76, v77
	ds_write_b16 v154, v1 offset:36864
	ds_write_b16_d16_hi v154, v1 offset:37120
	v_lshlrev_b32_e32 v82, 16, v201
	v_lshlrev_b32_e32 v83, 16, v202
	v_pk_mul_f32 v[90:91], v[82:83], v[82:83]
	s_nop 0
	v_pk_fma_f32 v[90:91], v[90:91], s[86:87], v[104:105] op_sel_hi:[1, 0, 0] neg_lo:[1, 0, 0] neg_hi:[1, 0, 0]
	s_nop 0
	v_pk_mul_f32 v[90:91], v[90:91], v[82:83]
	s_nop 0
	v_exp_f32_e32 v90, v90
	v_exp_f32_e32 v91, v91
	s_nop 0
	v_pk_add_f32 v[90:91], v[90:91], 1.0 op_sel_hi:[1, 0]
	s_nop 0
	v_rcp_f32_e32 v90, v90
	v_rcp_f32_e32 v91, v91
	s_nop 0
	v_pk_mul_f32 v[80:81], v[90:91], v[82:83]
	s_nop 0
	v_pk_mul_f32 v[78:79], v[78:79], v[80:81]
	s_nop 0
	v_cvt_pk_bf16_f32 v1, v78, v79
	ds_write_b16 v154, v1 offset:37376
	ds_write_b16_d16_hi v154, v1 offset:37632
	v_lshlrev_b32_e32 v80, 16, v203
	v_lshlrev_b32_e32 v81, 16, v204
	v_pk_mul_f32 v[82:83], v[80:81], v[80:81]
	s_nop 0
	v_pk_fma_f32 v[82:83], v[82:83], s[86:87], v[104:105] op_sel_hi:[1, 0, 0] neg_lo:[1, 0, 0] neg_hi:[1, 0, 0]
	s_nop 0
	v_pk_mul_f32 v[82:83], v[82:83], v[80:81]
	s_nop 0
	v_exp_f32_e32 v82, v82
	v_exp_f32_e32 v83, v83
	s_nop 0
	v_pk_add_f32 v[74:75], v[82:83], 1.0 op_sel_hi:[1, 0]
	s_nop 0
	v_rcp_f32_e32 v74, v74
	v_rcp_f32_e32 v75, v75
	s_nop 0
	v_pk_mul_f32 v[74:75], v[74:75], v[80:81]
	s_nop 0
	v_pk_mul_f32 v[74:75], v[72:73], v[74:75]
	s_nop 0
	v_cvt_pk_bf16_f32 v1, v74, v75
	ds_write_b16 v154, v1 offset:37888
	ds_write_b16_d16_hi v154, v1 offset:38144
	s_cbranch_vccnz .LBB0_2340
; template <int MODE>
; __device__ __forceinline__ void rnn_phase(const RnnP& P, LAS unsigned char* lds, int G, int bid, int nunits) {
;     ...
;                 if (ip == 7) { const float h = h2.y; if (samp) P.o_rhs[(size_t)((R0 >> 4) + rg) * 2048 + chg] = h; else if (c == NCH - 1 && rg == 0) P.o_rhp[chg] = h; } }
	s_ashr_i32 s40, s0, 4
	v_add_u32_e32 v80, s40, v124
	v_ashrrev_i32_e32 v81, 31, v80
	v_lshlrev_b64 v[80:81], 13, v[80:81]
	v_lshl_add_u64 v[80:81], s[78:79], 0, v[80:81]
	s_mov_b64 s[40:41], -1
	s_cbranch_execz .LBB0_2341
	s_branch .LBB0_2342

; #define LAS __attribute__((address_space(3)))
; template <int MODE>
; __device__ __forceinline__ void rnn_phase(const RnnP& P, LAS unsigned char* lds, int G, int bid, int nunits) {
;     ...
;         for (int k = 0; k < 3; ++k) { const int i = tid + k * NTHR; if (i < 67 * 16) { const int j = i >> 4, cc = i & 15; const v4u v = pre.x[k]; f32x4 a, b;
;             a.x = __builtin_bit_cast(float, v.x << 16); a.y = __builtin_bit_cast(float, v.x & 0xffff0000u); a.z = __builtin_bit_cast(float, v.y << 16); a.w = __builtin_bit_cast(float, v.y & 0xffff0000u);
;             b.x = __builtin_bit_cast(float, v.z << 16); b.y = __builtin_bit_cast(float, v.z & 0xffff0000u); b.z = __builtin_bit_cast(float, v.w << 16); b.w = __builtin_bit_cast(float, v.w & 0xffff0000u);
;             *(LAS f32x4*)(XRF + j * 128 + cc * 8) = a; *(LAS f32x4*)(XRF + j * 128 + cc * 8 + 4) = b; } }
.LBB0_2350:
	v_lshlrev_b32_e32 v70, 16, v6
	v_and_b32_e32 v71, 0xffff0000, v6
	v_lshlrev_b32_e32 v72, 16, v7
	v_and_b32_e32 v73, 0xffff0000, v7
	v_lshlrev_b32_e32 v74, 16, v8
	v_and_b32_e32 v75, 0xffff0000, v8
	v_lshlrev_b32_e32 v76, 16, v9
	v_and_b32_e32 v77, 0xffff0000, v9
	ds_write_b128 v130, v[70:73]
	ds_write_b128 v130, v[74:77] offset:16
	s_or_b64 exec, exec, s[40:41]
	s_and_saveexec_b64 s[40:41], s[10:11]
	s_cbranch_execnz .LBB0_2311
	s_branch .LBB0_2312
